# dftl mainloops moved to the LDS-DMA core (two instances: K=2048 and K=512 tiles)
# baseline (speedup 1.0000x reference)
.LBB0_1196:
	s_cmp_gt_i32 s60, 12
	s_cselect_b64 s[2:3], -1, 0
	s_cmp_lt_i32 s61, 12
	s_cselect_b64 s[4:5], -1, 0
	s_or_b64 s[2:3], s[2:3], s[4:5]
	s_and_b64 vcc, exec, s[2:3]
	s_cbranch_vccnz .LBB0_1260
	s_mov_b64 s[4:5], s[0:1]
	s_cmpk_gt_i32 s58, 0x1ff
	s_cbranch_scc1 .LBB0_1206
	s_load_dwordx2 s[4:5], s[4:5], 0xe0
	v_xor_b32_e32 v5, v163, v162
	v_lshlrev_b32_e32 v5, 4, v5
	v_and_b32_e32 v3, 15, v162
	v_lshrrev_b32_e32 v129, 3, v162
	v_and_b32_e32 v5, 0x70, v5
	v_lshrrev_b32_e32 v2, 7, v162
	v_lshl_or_b32 v136, v129, 7, v5
	v_lshlrev_b32_e32 v5, 7, v3
	v_bfe_u32 v4, v162, 4, 2
	v_mov_b32_e32 v97, 0
	v_lshl_or_b32 v7, v2, 13, v5
	v_lshlrev_b32_e32 v2, 6, v2
	v_lshlrev_b32_e32 v96, 1, v3
	v_lshl_or_b32 v141, v4, 2, v2
	s_waitcnt lgkmcnt(0)
	v_lshl_add_u64 v[2:3], s[4:5], 0, v[96:97]
	s_mov_b64 s[2:3], 0x9b7a100
	v_lshl_add_u64 v[98:99], v[2:3], 0, s[2:3]
	s_add_u32 s3, s4, 0x6a80000
	s_addc_u32 s44, s5, 0
	s_add_u32 s45, s4, 0xab7a100
	v_bfe_u32 v6, v162, 1, 3
	s_load_dword s2, s[0:1], 0xf0
	s_addc_u32 s46, s5, 0
	v_bfe_u32 v1, v162, 6, 1
	v_bitop3_b32 v6, v163, v6, 3 bitop3:0x6c
	s_add_u32 s47, s4, 0x6680000
	v_lshlrev_b32_e32 v0, 3, v162
	v_lshl_or_b32 v5, v1, 13, v5
	v_lshlrev_b32_e32 v6, 4, v6
	s_addc_u32 s48, s5, 0
	v_and_b32_e32 v0, 56, v0
	v_or_b32_e32 v137, v7, v6
	v_or_b32_e32 v138, v5, v6
	v_xor_b32_e32 v6, 64, v6
	v_lshlrev_b32_e32 v1, 6, v1
	s_add_u32 s49, s4, 0xbb7a100
	v_or_b32_e32 v139, v7, v6
	v_or_b32_e32 v140, v5, v6
	s_addc_u32 s50, s5, 0
	s_mov_b32 s5, 0
	v_lshlrev_b32_e32 v100, 1, v0
	v_mov_b32_e32 v101, v97
	s_mov_b64 s[6:7], 0x100
	v_lshlrev_b32_e32 v142, 1, v1
	s_mov_b64 s[8:9], 0x1000
	s_mov_b64 s[10:11], 0x1800
	s_mov_b64 s[12:13], 0x8000
	s_mov_b32 s51, 0x8000
	s_mov_b64 s[14:15], 0x8800
	s_mov_b64 s[16:17], 0x9000
	s_mov_b32 s54, 0x9000
	s_mov_b64 s[18:19], 0x9800
	s_mov_b64 s[20:21], 0x10000
	s_mov_b32 s55, 0x10000
	s_mov_b64 s[22:23], 0x10800
	s_mov_b64 s[24:25], 0x11000
	s_mov_b32 s59, 0x11000
	s_mov_b64 s[26:27], 0x11800
	s_mov_b64 s[28:29], 0x18000
	s_mov_b32 s62, 0x18000
	s_mov_b64 s[30:31], 0x18800
	s_mov_b64 s[34:35], 0x19000
	s_mov_b32 s63, 0x19000
	s_mov_b64 s[36:37], 0x19800
	s_mov_b32 s64, s58
	v_and_b32_e32 v240, 63, v162
	v_lshrrev_b32_e32 v247, 6, v162
	v_lshrrev_b32_e32 v242, 3, v240
	v_lshl_add_u32 v242, v247, 5, v242
	v_and_b32_e32 v243, 7, v240
	v_lshrrev_b32_e32 v244, 4, v240
	v_xor_b32_e32 v243, v243, v244
	v_lshlrev_b32_e32 v243, 4, v243
	v_mov_b32_e32 v241, 0x1000
	v_mad_u32_u24 v248, v242, v241, v243
	v_xor_b32_e32 v249, 64, v248
	v_add_u32_e32 v249, 0x8000, v249
	v_add_u32_e32 v250, 0x10000, v248
	v_xor_b32_e32 v251, 64, v248
	v_add_u32_e32 v251, 0x18000, v251
	v_and_b32_e32 v241, 15, v240
	v_lshrrev_b32_e32 v242, 1, v241
	v_xor_b32_e32 v242, v242, v244
	v_lshlrev_b32_e32 v242, 4, v242
	v_lshl_or_b32 v242, v241, 7, v242
	v_lshrrev_b32_e32 v243, 1, v247
	v_lshl_or_b32 v252, v243, 13, v242
	v_xor_b32_e32 v253, 64, v252
	v_and_b32_e32 v243, 1, v247
	v_lshl_or_b32 v254, v243, 13, v242
	v_xor_b32_e32 v255, 64, v254
	v_and_b32_e32 v240, 63, v162
	v_lshrrev_b32_e32 v247, 6, v162
	v_lshrrev_b32_e32 v242, 3, v240
	v_lshl_add_u32 v242, v247, 5, v242
	v_and_b32_e32 v243, 7, v240
	v_lshrrev_b32_e32 v244, 4, v240
	v_xor_b32_e32 v243, v243, v244
	v_lshlrev_b32_e32 v243, 4, v243
	v_mov_b32_e32 v241, 0x400
	v_mad_u32_u24 v236, v242, v241, v243
	v_xor_b32_e32 v237, 64, v236
	v_add_u32_e32 v237, 0x2000, v237
	v_add_u32_e32 v238, 0x4000, v236
	v_xor_b32_e32 v239, 64, v236
	v_add_u32_e32 v239, 0x6000, v239
	v_and_b32_e32 v241, 15, v240
	v_lshrrev_b32_e32 v242, 1, v241
	v_xor_b32_e32 v242, v242, v244
	v_lshlrev_b32_e32 v242, 4, v242
	v_lshl_or_b32 v242, v241, 7, v242
	v_lshrrev_b32_e32 v243, 1, v247
	v_lshl_or_b32 v252, v243, 13, v242
	v_xor_b32_e32 v253, 64, v252
	v_and_b32_e32 v243, 1, v247
	v_lshl_or_b32 v254, v243, 13, v242
	v_xor_b32_e32 v255, 64, v254

.LBB0_1203:
	v_mul_u32_u24_e32 v0, s4, v129
	v_lshlrev_b32_e32 v96, 1, v0
	v_lshl_add_u64 v[0:1], s[38:39], 0, v[96:97]
	v_lshl_add_u64 v[102:103], v[0:1], 0, v[100:101]
	v_lshl_add_u64 v[0:1], s[40:41], 0, v[96:97]
	v_lshl_add_u64 v[104:105], v[0:1], 0, v[100:101]
	s_lshl_b32 s38, s4, 6
	s_mov_b32 s39, s5
	v_lshl_add_u64 v[2:3], v[102:103], 0, s[38:39]
	v_lshl_add_u64 v[6:7], v[104:105], 0, s[38:39]
	v_lshl_add_u64 v[4:5], v[2:3], 0, s[38:39]
	v_lshl_add_u64 v[12:13], v[6:7], 0, s[38:39]
	v_lshl_add_u64 v[88:89], v[4:5], 0, s[38:39]
	v_lshl_add_u64 v[90:91], v[12:13], 0, s[38:39]
	s_lshr_b32 s42, s4, 6
	s_lshl_b32 s40, s4, 5
	s_lshl_b32 s4, s4, 7
	s_add_i32 s67, s42, -1
	s_sub_u32 s68, 0, s4
	s_subb_u32 s69, 0, 0
	v_lshl_add_u64 v[106:107], v[88:89], 0, s[68:69]
	v_lshl_add_u64 v[108:109], v[90:91], 0, s[68:69]
	v_lshl_add_u64 v[110:111], v[106:107], 0, s[38:39]
	v_lshl_add_u64 v[112:113], v[108:109], 0, s[38:39]
	v_mov_b32_e32 v8, 0
	v_lshl_add_u64 v[114:115], v[110:111], 0, s[38:39]
	v_lshl_add_u64 v[116:117], v[112:113], 0, s[38:39]
	s_mov_b32 s43, 0
	s_mov_b32 s41, s5
	v_mov_b32_e32 v9, v8
	v_mov_b32_e32 v10, v8
	v_mov_b32_e32 v11, v8
	v_mov_b32_e32 v16, v8
	v_mov_b32_e32 v17, v8
	v_mov_b32_e32 v18, v8
	v_mov_b32_e32 v19, v8
	v_mov_b32_e32 v24, v8
	v_mov_b32_e32 v25, v8
	v_mov_b32_e32 v26, v8
	v_mov_b32_e32 v27, v8
	v_mov_b32_e32 v0, v8
	v_mov_b32_e32 v1, v8
	v_mov_b32_e32 v2, v8
	v_mov_b32_e32 v3, v8
	v_mov_b32_e32 v12, v8
	v_mov_b32_e32 v13, v8
	v_mov_b32_e32 v14, v8
	v_mov_b32_e32 v15, v8
	v_mov_b32_e32 v4, v8
	v_mov_b32_e32 v5, v8
	v_mov_b32_e32 v6, v8
	v_mov_b32_e32 v7, v8
	s_lshl_b32 s40, s40, 1
	v_lshl_add_u64 v[118:119], v[104:105], 0, s[6:7]
	v_lshl_add_u64 v[120:121], v[102:103], 0, s[6:7]
	v_lshl_add_u64 v[122:123], v[108:109], 0, s[6:7]
	v_lshl_add_u64 v[124:125], v[106:107], 0, s[6:7]
	v_lshl_add_u64 v[126:127], v[112:113], 0, s[6:7]
	v_lshl_add_u64 v[132:133], v[110:111], 0, s[6:7]
	v_lshl_add_u64 v[130:131], v[116:117], 0, s[6:7]
	v_lshl_add_u64 v[134:135], v[114:115], 0, s[6:7]
	v_mov_b32_e32 v88, v8
	v_mov_b32_e32 v89, v8
	v_mov_b32_e32 v90, v8
	v_mov_b32_e32 v91, v8
	v_mov_b32_e32 v92, v8
	v_mov_b32_e32 v93, v8
	v_mov_b32_e32 v94, v8
	v_mov_b32_e32 v95, v8
	v_mov_b32_e32 v20, v8
	v_mov_b32_e32 v21, v8
	v_mov_b32_e32 v22, v8
	v_mov_b32_e32 v23, v8
	v_mov_b32_e32 v28, v8
	v_mov_b32_e32 v29, v8
	v_mov_b32_e32 v30, v8
	v_mov_b32_e32 v31, v8
	v_mov_b32_e32 v60, v8
	v_mov_b32_e32 v61, v8
	v_mov_b32_e32 v62, v8
	v_mov_b32_e32 v63, v8
	v_mov_b32_e32 v68, v8
	v_mov_b32_e32 v69, v8
	v_mov_b32_e32 v70, v8
	v_mov_b32_e32 v71, v8
	v_mov_b32_e32 v72, v8
	v_mov_b32_e32 v73, v8
	v_mov_b32_e32 v74, v8
	v_mov_b32_e32 v75, v8
	v_mov_b32_e32 v76, v8
	v_mov_b32_e32 v77, v8
	v_mov_b32_e32 v78, v8
	v_mov_b32_e32 v79, v8
	v_mov_b32_e32 v80, v8
	v_mov_b32_e32 v81, v8
	v_mov_b32_e32 v82, v8
	v_mov_b32_e32 v83, v8
	v_mov_b32_e32 v84, v8
	v_mov_b32_e32 v85, v8
	v_mov_b32_e32 v86, v8
	v_mov_b32_e32 v87, v8
	s_cmpk_gt_i32 s64, 0xff
	s_cbranch_scc1 .Lg12_light
	v_readfirstlane_b32 s68, v102
	v_readfirstlane_b32 s69, v103
	v_readfirstlane_b32 s70, v104
	v_readfirstlane_b32 s71, v105
	v_readfirstlane_b32 s4, v247
	s_nop 3
	s_mul_i32 s67, s4, 0x8000
	s_sub_u32 s68, s68, s67
	s_subb_u32 s69, s69, 0
	s_sub_u32 s70, s70, s67
	s_subb_u32 s71, s71, 0
	s_lshl_b32 s4, s4, 12
	s_add_u32 m0, s4, 0x0
	v_mov_b32_e32 v92, 0
	global_load_lds_dwordx4 v248, s[68:69]
	v_mov_b32_e32 v93, 0
	s_add_u32 m0, s4, 0x400
	v_mov_b32_e32 v94, 0
	global_load_lds_dwordx4 v249, s[68:69]
	v_mov_b32_e32 v95, 0
	s_add_u32 m0, s4, 0x800
	v_mov_b32_e32 v88, 0
	global_load_lds_dwordx4 v250, s[68:69]
	v_mov_b32_e32 v89, 0
	s_add_u32 m0, s4, 0xc00
	v_mov_b32_e32 v90, 0
	global_load_lds_dwordx4 v251, s[68:69]
	v_mov_b32_e32 v91, 0
	s_add_u32 m0, s4, 0x8000
	v_mov_b32_e32 v84, 0
	global_load_lds_dwordx4 v248, s[70:71]
	v_mov_b32_e32 v85, 0
	s_add_u32 m0, s4, 0x8400
	v_mov_b32_e32 v86, 0
	global_load_lds_dwordx4 v249, s[70:71]
	v_mov_b32_e32 v87, 0
	s_add_u32 m0, s4, 0x8800
	v_mov_b32_e32 v80, 0
	global_load_lds_dwordx4 v250, s[70:71]
	v_mov_b32_e32 v81, 0
	s_add_u32 m0, s4, 0x8c00
	v_mov_b32_e32 v82, 0
	global_load_lds_dwordx4 v251, s[70:71]
	v_mov_b32_e32 v83, 0
	s_add_u32 s68, s68, 0x80
	s_addc_u32 s69, s69, 0
	s_add_u32 s70, s70, 0x80
	s_addc_u32 s71, s71, 0
	s_add_u32 m0, s4, 0x4000
	v_mov_b32_e32 v76, 0
	global_load_lds_dwordx4 v248, s[68:69]
	v_mov_b32_e32 v77, 0
	s_add_u32 m0, s4, 0x4400
	v_mov_b32_e32 v78, 0
	global_load_lds_dwordx4 v249, s[68:69]
	v_mov_b32_e32 v79, 0
	s_add_u32 m0, s4, 0x4800
	v_mov_b32_e32 v72, 0
	global_load_lds_dwordx4 v250, s[68:69]
	v_mov_b32_e32 v73, 0
	s_add_u32 m0, s4, 0x4c00
	v_mov_b32_e32 v74, 0
	global_load_lds_dwordx4 v251, s[68:69]
	v_mov_b32_e32 v75, 0
	s_add_u32 m0, s4, 0xc000
	v_mov_b32_e32 v68, 0
	global_load_lds_dwordx4 v248, s[70:71]
	v_mov_b32_e32 v69, 0
	s_add_u32 m0, s4, 0xc400
	v_mov_b32_e32 v70, 0
	global_load_lds_dwordx4 v249, s[70:71]
	v_mov_b32_e32 v71, 0
	s_add_u32 m0, s4, 0xc800
	v_mov_b32_e32 v60, 0
	global_load_lds_dwordx4 v250, s[70:71]
	v_mov_b32_e32 v61, 0
	s_add_u32 m0, s4, 0xcc00
	v_mov_b32_e32 v62, 0
	global_load_lds_dwordx4 v251, s[70:71]
	v_mov_b32_e32 v63, 0
	s_add_u32 s68, s68, 0x80
	s_addc_u32 s69, s69, 0
	s_add_u32 s70, s70, 0x80
	s_addc_u32 s71, s71, 0
	v_mov_b32_e32 v28, 0
	v_mov_b32_e32 v29, 0
	v_mov_b32_e32 v30, 0
	v_mov_b32_e32 v31, 0
	v_mov_b32_e32 v20, 0
	v_mov_b32_e32 v21, 0
	v_mov_b32_e32 v22, 0
	v_mov_b32_e32 v23, 0
	v_mov_b32_e32 v4, 0
	v_mov_b32_e32 v5, 0
	v_mov_b32_e32 v6, 0
	v_mov_b32_e32 v7, 0
	v_mov_b32_e32 v12, 0
	v_mov_b32_e32 v13, 0
	v_mov_b32_e32 v14, 0
	v_mov_b32_e32 v15, 0
	v_mov_b32_e32 v0, 0
	v_mov_b32_e32 v1, 0
	v_mov_b32_e32 v2, 0
	v_mov_b32_e32 v3, 0
	v_mov_b32_e32 v24, 0
	v_mov_b32_e32 v25, 0
	v_mov_b32_e32 v26, 0
	v_mov_b32_e32 v27, 0
	v_mov_b32_e32 v16, 0
	v_mov_b32_e32 v17, 0
	v_mov_b32_e32 v18, 0
	v_mov_b32_e32 v19, 0
	v_mov_b32_e32 v8, 0
	v_mov_b32_e32 v9, 0
	v_mov_b32_e32 v10, 0
	v_mov_b32_e32 v11, 0
	s_waitcnt vmcnt(8)
	s_barrier
	ds_read_b128 v[32:35], v252 offset:0
	ds_read_b128 v[104:107], v254 offset:32768
	ds_read_b128 v[108:111], v254 offset:34816
	ds_read_b128 v[112:115], v254 offset:36864
	ds_read_b128 v[116:119], v254 offset:38912
	ds_read_b128 v[36:39], v252 offset:2048
	ds_read_b128 v[40:43], v252 offset:4096
	ds_read_b128 v[44:47], v252 offset:6144
	ds_read_b128 v[48:51], v253 offset:0
	ds_read_b128 v[120:123], v255 offset:32768
	ds_read_b128 v[124:127], v255 offset:34816
	ds_read_b128 v[132:135], v255 offset:36864
	ds_read_b128 v[136:139], v255 offset:38912
	s_waitcnt lgkmcnt(11)
	v_mfma_f32_16x16x32_bf16 v[92:95], v[32:35], v[104:107], v[92:95]
	s_waitcnt lgkmcnt(10)
	v_mfma_f32_16x16x32_bf16 v[88:91], v[32:35], v[108:111], v[88:91]
	s_waitcnt lgkmcnt(9)
	v_mfma_f32_16x16x32_bf16 v[84:87], v[32:35], v[112:115], v[84:87]
	s_waitcnt lgkmcnt(8)
	v_mfma_f32_16x16x32_bf16 v[80:83], v[32:35], v[116:119], v[80:83]
	ds_read_b128 v[52:55], v253 offset:2048
	ds_read_b128 v[56:59], v253 offset:4096
	ds_read_b128 v[64:67], v253 offset:6144
	s_waitcnt lgkmcnt(10)
	v_mfma_f32_16x16x32_bf16 v[76:79], v[36:39], v[104:107], v[76:79]
	v_mfma_f32_16x16x32_bf16 v[72:75], v[36:39], v[108:111], v[72:75]
	v_mfma_f32_16x16x32_bf16 v[68:71], v[36:39], v[112:115], v[68:71]
	v_mfma_f32_16x16x32_bf16 v[60:63], v[36:39], v[116:119], v[60:63]
	s_waitcnt lgkmcnt(0)
	s_barrier
	s_add_u32 m0, s4, 0x0
	v_mfma_f32_16x16x32_bf16 v[28:31], v[40:43], v[104:107], v[28:31]
	global_load_lds_dwordx4 v248, s[68:69]
	s_add_u32 m0, s4, 0x400
	v_mfma_f32_16x16x32_bf16 v[20:23], v[40:43], v[108:111], v[20:23]
	global_load_lds_dwordx4 v249, s[68:69]
	s_add_u32 m0, s4, 0x800
	v_mfma_f32_16x16x32_bf16 v[4:7], v[40:43], v[112:115], v[4:7]
	global_load_lds_dwordx4 v250, s[68:69]
	s_add_u32 m0, s4, 0xc00
	v_mfma_f32_16x16x32_bf16 v[12:15], v[40:43], v[116:119], v[12:15]
	global_load_lds_dwordx4 v251, s[68:69]
	s_add_u32 m0, s4, 0x8000
	v_mfma_f32_16x16x32_bf16 v[0:3], v[44:47], v[104:107], v[0:3]
	global_load_lds_dwordx4 v248, s[70:71]
	s_add_u32 m0, s4, 0x8400
	v_mfma_f32_16x16x32_bf16 v[24:27], v[44:47], v[108:111], v[24:27]
	global_load_lds_dwordx4 v249, s[70:71]
	s_add_u32 m0, s4, 0x8800
	v_mfma_f32_16x16x32_bf16 v[16:19], v[44:47], v[112:115], v[16:19]
	global_load_lds_dwordx4 v250, s[70:71]
	s_add_u32 m0, s4, 0x8c00
	v_mfma_f32_16x16x32_bf16 v[8:11], v[44:47], v[116:119], v[8:11]
	global_load_lds_dwordx4 v251, s[70:71]
	s_add_u32 s68, s68, 0x80
	s_addc_u32 s69, s69, 0
	s_add_u32 s70, s70, 0x80
	s_addc_u32 s71, s71, 0
	s_waitcnt vmcnt(8)
	s_barrier
	ds_read_b128 v[32:35], v252 offset:16384
	ds_read_b128 v[104:107], v254 offset:49152
	ds_read_b128 v[108:111], v254 offset:51200
	ds_read_b128 v[112:115], v254 offset:53248
	ds_read_b128 v[116:119], v254 offset:55296
	ds_read_b128 v[36:39], v252 offset:18432
	ds_read_b128 v[40:43], v252 offset:20480
	ds_read_b128 v[44:47], v252 offset:22528
	v_mfma_f32_16x16x32_bf16 v[92:95], v[48:51], v[120:123], v[92:95]
	v_mfma_f32_16x16x32_bf16 v[88:91], v[48:51], v[124:127], v[88:91]
	v_mfma_f32_16x16x32_bf16 v[84:87], v[48:51], v[132:135], v[84:87]
	v_mfma_f32_16x16x32_bf16 v[80:83], v[48:51], v[136:139], v[80:83]
	v_mfma_f32_16x16x32_bf16 v[76:79], v[52:55], v[120:123], v[76:79]
	v_mfma_f32_16x16x32_bf16 v[72:75], v[52:55], v[124:127], v[72:75]
	v_mfma_f32_16x16x32_bf16 v[68:71], v[52:55], v[132:135], v[68:71]
	v_mfma_f32_16x16x32_bf16 v[60:63], v[52:55], v[136:139], v[60:63]
	v_mfma_f32_16x16x32_bf16 v[28:31], v[56:59], v[120:123], v[28:31]
	v_mfma_f32_16x16x32_bf16 v[20:23], v[56:59], v[124:127], v[20:23]
	v_mfma_f32_16x16x32_bf16 v[4:7], v[56:59], v[132:135], v[4:7]
	v_mfma_f32_16x16x32_bf16 v[12:15], v[56:59], v[136:139], v[12:15]
	v_mfma_f32_16x16x32_bf16 v[0:3], v[64:67], v[120:123], v[0:3]
	v_mfma_f32_16x16x32_bf16 v[24:27], v[64:67], v[124:127], v[24:27]
	v_mfma_f32_16x16x32_bf16 v[16:19], v[64:67], v[132:135], v[16:19]
	v_mfma_f32_16x16x32_bf16 v[8:11], v[64:67], v[136:139], v[8:11]
	ds_read_b128 v[48:51], v253 offset:16384
	ds_read_b128 v[120:123], v255 offset:49152
	ds_read_b128 v[124:127], v255 offset:51200
	ds_read_b128 v[132:135], v255 offset:53248
	ds_read_b128 v[136:139], v255 offset:55296
	ds_read_b128 v[52:55], v253 offset:18432
	ds_read_b128 v[56:59], v253 offset:20480
	ds_read_b128 v[64:67], v253 offset:22528
	s_waitcnt lgkmcnt(14)
	v_mfma_f32_16x16x32_bf16 v[92:95], v[32:35], v[104:107], v[92:95]
	s_waitcnt lgkmcnt(13)
	v_mfma_f32_16x16x32_bf16 v[88:91], v[32:35], v[108:111], v[88:91]
	s_waitcnt lgkmcnt(12)
	v_mfma_f32_16x16x32_bf16 v[84:87], v[32:35], v[112:115], v[84:87]
	s_waitcnt lgkmcnt(11)
	v_mfma_f32_16x16x32_bf16 v[80:83], v[32:35], v[116:119], v[80:83]
	s_waitcnt lgkmcnt(10)
	v_mfma_f32_16x16x32_bf16 v[76:79], v[36:39], v[104:107], v[76:79]
	v_mfma_f32_16x16x32_bf16 v[72:75], v[36:39], v[108:111], v[72:75]
	v_mfma_f32_16x16x32_bf16 v[68:71], v[36:39], v[112:115], v[68:71]
	v_mfma_f32_16x16x32_bf16 v[60:63], v[36:39], v[116:119], v[60:63]
	s_waitcnt lgkmcnt(0)
	s_barrier
	s_add_u32 m0, s4, 0x4000
	v_mfma_f32_16x16x32_bf16 v[28:31], v[40:43], v[104:107], v[28:31]
	global_load_lds_dwordx4 v248, s[68:69]
	s_add_u32 m0, s4, 0x4400
	v_mfma_f32_16x16x32_bf16 v[20:23], v[40:43], v[108:111], v[20:23]
	global_load_lds_dwordx4 v249, s[68:69]
	s_add_u32 m0, s4, 0x4800
	v_mfma_f32_16x16x32_bf16 v[4:7], v[40:43], v[112:115], v[4:7]
	global_load_lds_dwordx4 v250, s[68:69]
	s_add_u32 m0, s4, 0x4c00
	v_mfma_f32_16x16x32_bf16 v[12:15], v[40:43], v[116:119], v[12:15]
	global_load_lds_dwordx4 v251, s[68:69]
	s_add_u32 m0, s4, 0xc000
	v_mfma_f32_16x16x32_bf16 v[0:3], v[44:47], v[104:107], v[0:3]
	global_load_lds_dwordx4 v248, s[70:71]
	s_add_u32 m0, s4, 0xc400
	v_mfma_f32_16x16x32_bf16 v[24:27], v[44:47], v[108:111], v[24:27]
	global_load_lds_dwordx4 v249, s[70:71]
	s_add_u32 m0, s4, 0xc800
	v_mfma_f32_16x16x32_bf16 v[16:19], v[44:47], v[112:115], v[16:19]
	global_load_lds_dwordx4 v250, s[70:71]
	s_add_u32 m0, s4, 0xcc00
	v_mfma_f32_16x16x32_bf16 v[8:11], v[44:47], v[116:119], v[8:11]
	global_load_lds_dwordx4 v251, s[70:71]
	s_add_u32 s68, s68, 0x80
	s_addc_u32 s69, s69, 0
	s_add_u32 s70, s70, 0x80
	s_addc_u32 s71, s71, 0
	s_mov_b32 s32, 14
.Lg12_loop:
	s_waitcnt vmcnt(8)
	s_barrier
	ds_read_b128 v[32:35], v252 offset:0
	ds_read_b128 v[104:107], v254 offset:32768
	ds_read_b128 v[108:111], v254 offset:34816
	ds_read_b128 v[112:115], v254 offset:36864
	ds_read_b128 v[116:119], v254 offset:38912
	ds_read_b128 v[36:39], v252 offset:2048
	ds_read_b128 v[40:43], v252 offset:4096
	ds_read_b128 v[44:47], v252 offset:6144
	v_mfma_f32_16x16x32_bf16 v[92:95], v[48:51], v[120:123], v[92:95]
	v_mfma_f32_16x16x32_bf16 v[88:91], v[48:51], v[124:127], v[88:91]
	v_mfma_f32_16x16x32_bf16 v[84:87], v[48:51], v[132:135], v[84:87]
	v_mfma_f32_16x16x32_bf16 v[80:83], v[48:51], v[136:139], v[80:83]
	v_mfma_f32_16x16x32_bf16 v[76:79], v[52:55], v[120:123], v[76:79]
	v_mfma_f32_16x16x32_bf16 v[72:75], v[52:55], v[124:127], v[72:75]
	v_mfma_f32_16x16x32_bf16 v[68:71], v[52:55], v[132:135], v[68:71]
	v_mfma_f32_16x16x32_bf16 v[60:63], v[52:55], v[136:139], v[60:63]
	v_mfma_f32_16x16x32_bf16 v[28:31], v[56:59], v[120:123], v[28:31]
	v_mfma_f32_16x16x32_bf16 v[20:23], v[56:59], v[124:127], v[20:23]
	v_mfma_f32_16x16x32_bf16 v[4:7], v[56:59], v[132:135], v[4:7]
	v_mfma_f32_16x16x32_bf16 v[12:15], v[56:59], v[136:139], v[12:15]
	v_mfma_f32_16x16x32_bf16 v[0:3], v[64:67], v[120:123], v[0:3]
	v_mfma_f32_16x16x32_bf16 v[24:27], v[64:67], v[124:127], v[24:27]
	v_mfma_f32_16x16x32_bf16 v[16:19], v[64:67], v[132:135], v[16:19]
	v_mfma_f32_16x16x32_bf16 v[8:11], v[64:67], v[136:139], v[8:11]
	ds_read_b128 v[48:51], v253 offset:0
	ds_read_b128 v[120:123], v255 offset:32768
	ds_read_b128 v[124:127], v255 offset:34816
	ds_read_b128 v[132:135], v255 offset:36864
	ds_read_b128 v[136:139], v255 offset:38912
	ds_read_b128 v[52:55], v253 offset:2048
	ds_read_b128 v[56:59], v253 offset:4096
	ds_read_b128 v[64:67], v253 offset:6144
	s_waitcnt lgkmcnt(14)
	v_mfma_f32_16x16x32_bf16 v[92:95], v[32:35], v[104:107], v[92:95]
	s_waitcnt lgkmcnt(13)
	v_mfma_f32_16x16x32_bf16 v[88:91], v[32:35], v[108:111], v[88:91]
	s_waitcnt lgkmcnt(12)
	v_mfma_f32_16x16x32_bf16 v[84:87], v[32:35], v[112:115], v[84:87]
	s_waitcnt lgkmcnt(11)
	v_mfma_f32_16x16x32_bf16 v[80:83], v[32:35], v[116:119], v[80:83]
	s_waitcnt lgkmcnt(10)
	v_mfma_f32_16x16x32_bf16 v[76:79], v[36:39], v[104:107], v[76:79]
	v_mfma_f32_16x16x32_bf16 v[72:75], v[36:39], v[108:111], v[72:75]
	v_mfma_f32_16x16x32_bf16 v[68:71], v[36:39], v[112:115], v[68:71]
	v_mfma_f32_16x16x32_bf16 v[60:63], v[36:39], v[116:119], v[60:63]
	s_waitcnt lgkmcnt(0)
	s_barrier
	s_add_u32 m0, s4, 0x0
	v_mfma_f32_16x16x32_bf16 v[28:31], v[40:43], v[104:107], v[28:31]
	global_load_lds_dwordx4 v248, s[68:69]
	s_add_u32 m0, s4, 0x400
	v_mfma_f32_16x16x32_bf16 v[20:23], v[40:43], v[108:111], v[20:23]
	global_load_lds_dwordx4 v249, s[68:69]
	s_add_u32 m0, s4, 0x800
	v_mfma_f32_16x16x32_bf16 v[4:7], v[40:43], v[112:115], v[4:7]
	global_load_lds_dwordx4 v250, s[68:69]
	s_add_u32 m0, s4, 0xc00
	v_mfma_f32_16x16x32_bf16 v[12:15], v[40:43], v[116:119], v[12:15]
	global_load_lds_dwordx4 v251, s[68:69]
	s_add_u32 m0, s4, 0x8000
	v_mfma_f32_16x16x32_bf16 v[0:3], v[44:47], v[104:107], v[0:3]
	global_load_lds_dwordx4 v248, s[70:71]
	s_add_u32 m0, s4, 0x8400
	v_mfma_f32_16x16x32_bf16 v[24:27], v[44:47], v[108:111], v[24:27]
	global_load_lds_dwordx4 v249, s[70:71]
	s_add_u32 m0, s4, 0x8800
	v_mfma_f32_16x16x32_bf16 v[16:19], v[44:47], v[112:115], v[16:19]
	global_load_lds_dwordx4 v250, s[70:71]
	s_add_u32 m0, s4, 0x8c00
	v_mfma_f32_16x16x32_bf16 v[8:11], v[44:47], v[116:119], v[8:11]
	global_load_lds_dwordx4 v251, s[70:71]
	s_add_u32 s68, s68, 0x80
	s_addc_u32 s69, s69, 0
	s_add_u32 s70, s70, 0x80
	s_addc_u32 s71, s71, 0
	s_waitcnt vmcnt(8)
	s_barrier
	ds_read_b128 v[32:35], v252 offset:16384
	ds_read_b128 v[104:107], v254 offset:49152
	ds_read_b128 v[108:111], v254 offset:51200
	ds_read_b128 v[112:115], v254 offset:53248
	ds_read_b128 v[116:119], v254 offset:55296
	ds_read_b128 v[36:39], v252 offset:18432
	ds_read_b128 v[40:43], v252 offset:20480
	ds_read_b128 v[44:47], v252 offset:22528
	v_mfma_f32_16x16x32_bf16 v[92:95], v[48:51], v[120:123], v[92:95]
	v_mfma_f32_16x16x32_bf16 v[88:91], v[48:51], v[124:127], v[88:91]
	v_mfma_f32_16x16x32_bf16 v[84:87], v[48:51], v[132:135], v[84:87]
	v_mfma_f32_16x16x32_bf16 v[80:83], v[48:51], v[136:139], v[80:83]
	v_mfma_f32_16x16x32_bf16 v[76:79], v[52:55], v[120:123], v[76:79]
	v_mfma_f32_16x16x32_bf16 v[72:75], v[52:55], v[124:127], v[72:75]
	v_mfma_f32_16x16x32_bf16 v[68:71], v[52:55], v[132:135], v[68:71]
	v_mfma_f32_16x16x32_bf16 v[60:63], v[52:55], v[136:139], v[60:63]
	v_mfma_f32_16x16x32_bf16 v[28:31], v[56:59], v[120:123], v[28:31]
	v_mfma_f32_16x16x32_bf16 v[20:23], v[56:59], v[124:127], v[20:23]
	v_mfma_f32_16x16x32_bf16 v[4:7], v[56:59], v[132:135], v[4:7]
	v_mfma_f32_16x16x32_bf16 v[12:15], v[56:59], v[136:139], v[12:15]
	v_mfma_f32_16x16x32_bf16 v[0:3], v[64:67], v[120:123], v[0:3]
	v_mfma_f32_16x16x32_bf16 v[24:27], v[64:67], v[124:127], v[24:27]
	v_mfma_f32_16x16x32_bf16 v[16:19], v[64:67], v[132:135], v[16:19]
	v_mfma_f32_16x16x32_bf16 v[8:11], v[64:67], v[136:139], v[8:11]
	ds_read_b128 v[48:51], v253 offset:16384
	ds_read_b128 v[120:123], v255 offset:49152
	ds_read_b128 v[124:127], v255 offset:51200
	ds_read_b128 v[132:135], v255 offset:53248
	ds_read_b128 v[136:139], v255 offset:55296
	ds_read_b128 v[52:55], v253 offset:18432
	ds_read_b128 v[56:59], v253 offset:20480
	ds_read_b128 v[64:67], v253 offset:22528
	s_waitcnt lgkmcnt(14)
	v_mfma_f32_16x16x32_bf16 v[92:95], v[32:35], v[104:107], v[92:95]
	s_waitcnt lgkmcnt(13)
	v_mfma_f32_16x16x32_bf16 v[88:91], v[32:35], v[108:111], v[88:91]
	s_waitcnt lgkmcnt(12)
	v_mfma_f32_16x16x32_bf16 v[84:87], v[32:35], v[112:115], v[84:87]
	s_waitcnt lgkmcnt(11)
	v_mfma_f32_16x16x32_bf16 v[80:83], v[32:35], v[116:119], v[80:83]
	s_waitcnt lgkmcnt(10)
	v_mfma_f32_16x16x32_bf16 v[76:79], v[36:39], v[104:107], v[76:79]
	v_mfma_f32_16x16x32_bf16 v[72:75], v[36:39], v[108:111], v[72:75]
	v_mfma_f32_16x16x32_bf16 v[68:71], v[36:39], v[112:115], v[68:71]
	v_mfma_f32_16x16x32_bf16 v[60:63], v[36:39], v[116:119], v[60:63]
	s_waitcnt lgkmcnt(0)
	s_barrier
	s_add_u32 m0, s4, 0x4000
	v_mfma_f32_16x16x32_bf16 v[28:31], v[40:43], v[104:107], v[28:31]
	global_load_lds_dwordx4 v248, s[68:69]
	s_add_u32 m0, s4, 0x4400
	v_mfma_f32_16x16x32_bf16 v[20:23], v[40:43], v[108:111], v[20:23]
	global_load_lds_dwordx4 v249, s[68:69]
	s_add_u32 m0, s4, 0x4800
	v_mfma_f32_16x16x32_bf16 v[4:7], v[40:43], v[112:115], v[4:7]
	global_load_lds_dwordx4 v250, s[68:69]
	s_add_u32 m0, s4, 0x4c00
	v_mfma_f32_16x16x32_bf16 v[12:15], v[40:43], v[116:119], v[12:15]
	global_load_lds_dwordx4 v251, s[68:69]
	s_add_u32 m0, s4, 0xc000
	v_mfma_f32_16x16x32_bf16 v[0:3], v[44:47], v[104:107], v[0:3]
	global_load_lds_dwordx4 v248, s[70:71]
	s_add_u32 m0, s4, 0xc400
	v_mfma_f32_16x16x32_bf16 v[24:27], v[44:47], v[108:111], v[24:27]
	global_load_lds_dwordx4 v249, s[70:71]
	s_add_u32 m0, s4, 0xc800
	v_mfma_f32_16x16x32_bf16 v[16:19], v[44:47], v[112:115], v[16:19]
	global_load_lds_dwordx4 v250, s[70:71]
	s_add_u32 m0, s4, 0xcc00
	v_mfma_f32_16x16x32_bf16 v[8:11], v[44:47], v[116:119], v[8:11]
	global_load_lds_dwordx4 v251, s[70:71]
	s_add_u32 s68, s68, 0x80
	s_addc_u32 s69, s69, 0
	s_add_u32 s70, s70, 0x80
	s_addc_u32 s71, s71, 0
	s_sub_u32 s32, s32, 1
	s_cmp_lg_u32 s32, 0
	s_cbranch_scc1 .Lg12_loop
	s_waitcnt vmcnt(8)
	s_barrier
	ds_read_b128 v[32:35], v252 offset:0
	ds_read_b128 v[104:107], v254 offset:32768
	ds_read_b128 v[108:111], v254 offset:34816
	ds_read_b128 v[112:115], v254 offset:36864
	ds_read_b128 v[116:119], v254 offset:38912
	ds_read_b128 v[36:39], v252 offset:2048
	ds_read_b128 v[40:43], v252 offset:4096
	ds_read_b128 v[44:47], v252 offset:6144
	v_mfma_f32_16x16x32_bf16 v[92:95], v[48:51], v[120:123], v[92:95]
	v_mfma_f32_16x16x32_bf16 v[88:91], v[48:51], v[124:127], v[88:91]
	v_mfma_f32_16x16x32_bf16 v[84:87], v[48:51], v[132:135], v[84:87]
	v_mfma_f32_16x16x32_bf16 v[80:83], v[48:51], v[136:139], v[80:83]
	v_mfma_f32_16x16x32_bf16 v[76:79], v[52:55], v[120:123], v[76:79]
	v_mfma_f32_16x16x32_bf16 v[72:75], v[52:55], v[124:127], v[72:75]
	v_mfma_f32_16x16x32_bf16 v[68:71], v[52:55], v[132:135], v[68:71]
	v_mfma_f32_16x16x32_bf16 v[60:63], v[52:55], v[136:139], v[60:63]
	v_mfma_f32_16x16x32_bf16 v[28:31], v[56:59], v[120:123], v[28:31]
	v_mfma_f32_16x16x32_bf16 v[20:23], v[56:59], v[124:127], v[20:23]
	v_mfma_f32_16x16x32_bf16 v[4:7], v[56:59], v[132:135], v[4:7]
	v_mfma_f32_16x16x32_bf16 v[12:15], v[56:59], v[136:139], v[12:15]
	v_mfma_f32_16x16x32_bf16 v[0:3], v[64:67], v[120:123], v[0:3]
	v_mfma_f32_16x16x32_bf16 v[24:27], v[64:67], v[124:127], v[24:27]
	v_mfma_f32_16x16x32_bf16 v[16:19], v[64:67], v[132:135], v[16:19]
	v_mfma_f32_16x16x32_bf16 v[8:11], v[64:67], v[136:139], v[8:11]
	ds_read_b128 v[48:51], v253 offset:0
	ds_read_b128 v[120:123], v255 offset:32768
	ds_read_b128 v[124:127], v255 offset:34816
	ds_read_b128 v[132:135], v255 offset:36864
	ds_read_b128 v[136:139], v255 offset:38912
	ds_read_b128 v[52:55], v253 offset:2048
	ds_read_b128 v[56:59], v253 offset:4096
	ds_read_b128 v[64:67], v253 offset:6144
	s_waitcnt lgkmcnt(14)
	v_mfma_f32_16x16x32_bf16 v[92:95], v[32:35], v[104:107], v[92:95]
	s_waitcnt lgkmcnt(13)
	v_mfma_f32_16x16x32_bf16 v[88:91], v[32:35], v[108:111], v[88:91]
	s_waitcnt lgkmcnt(12)
	v_mfma_f32_16x16x32_bf16 v[84:87], v[32:35], v[112:115], v[84:87]
	s_waitcnt lgkmcnt(11)
	v_mfma_f32_16x16x32_bf16 v[80:83], v[32:35], v[116:119], v[80:83]
	s_waitcnt lgkmcnt(10)
	v_mfma_f32_16x16x32_bf16 v[76:79], v[36:39], v[104:107], v[76:79]
	v_mfma_f32_16x16x32_bf16 v[72:75], v[36:39], v[108:111], v[72:75]
	v_mfma_f32_16x16x32_bf16 v[68:71], v[36:39], v[112:115], v[68:71]
	v_mfma_f32_16x16x32_bf16 v[60:63], v[36:39], v[116:119], v[60:63]
	s_waitcnt lgkmcnt(0)
	s_barrier
	v_mfma_f32_16x16x32_bf16 v[28:31], v[40:43], v[104:107], v[28:31]
	v_mfma_f32_16x16x32_bf16 v[20:23], v[40:43], v[108:111], v[20:23]
	v_mfma_f32_16x16x32_bf16 v[4:7], v[40:43], v[112:115], v[4:7]
	v_mfma_f32_16x16x32_bf16 v[12:15], v[40:43], v[116:119], v[12:15]
	v_mfma_f32_16x16x32_bf16 v[0:3], v[44:47], v[104:107], v[0:3]
	v_mfma_f32_16x16x32_bf16 v[24:27], v[44:47], v[108:111], v[24:27]
	v_mfma_f32_16x16x32_bf16 v[16:19], v[44:47], v[112:115], v[16:19]
	v_mfma_f32_16x16x32_bf16 v[8:11], v[44:47], v[116:119], v[8:11]
	s_waitcnt vmcnt(0)
	s_barrier
	ds_read_b128 v[32:35], v252 offset:16384
	ds_read_b128 v[104:107], v254 offset:49152
	ds_read_b128 v[108:111], v254 offset:51200
	ds_read_b128 v[112:115], v254 offset:53248
	ds_read_b128 v[116:119], v254 offset:55296
	ds_read_b128 v[36:39], v252 offset:18432
	ds_read_b128 v[40:43], v252 offset:20480
	ds_read_b128 v[44:47], v252 offset:22528
	v_mfma_f32_16x16x32_bf16 v[92:95], v[48:51], v[120:123], v[92:95]
	v_mfma_f32_16x16x32_bf16 v[88:91], v[48:51], v[124:127], v[88:91]
	v_mfma_f32_16x16x32_bf16 v[84:87], v[48:51], v[132:135], v[84:87]
	v_mfma_f32_16x16x32_bf16 v[80:83], v[48:51], v[136:139], v[80:83]
	v_mfma_f32_16x16x32_bf16 v[76:79], v[52:55], v[120:123], v[76:79]
	v_mfma_f32_16x16x32_bf16 v[72:75], v[52:55], v[124:127], v[72:75]
	v_mfma_f32_16x16x32_bf16 v[68:71], v[52:55], v[132:135], v[68:71]
	v_mfma_f32_16x16x32_bf16 v[60:63], v[52:55], v[136:139], v[60:63]
	v_mfma_f32_16x16x32_bf16 v[28:31], v[56:59], v[120:123], v[28:31]
	v_mfma_f32_16x16x32_bf16 v[20:23], v[56:59], v[124:127], v[20:23]
	v_mfma_f32_16x16x32_bf16 v[4:7], v[56:59], v[132:135], v[4:7]
	v_mfma_f32_16x16x32_bf16 v[12:15], v[56:59], v[136:139], v[12:15]
	v_mfma_f32_16x16x32_bf16 v[0:3], v[64:67], v[120:123], v[0:3]
	v_mfma_f32_16x16x32_bf16 v[24:27], v[64:67], v[124:127], v[24:27]
	v_mfma_f32_16x16x32_bf16 v[16:19], v[64:67], v[132:135], v[16:19]
	v_mfma_f32_16x16x32_bf16 v[8:11], v[64:67], v[136:139], v[8:11]
	ds_read_b128 v[48:51], v253 offset:16384
	ds_read_b128 v[120:123], v255 offset:49152
	ds_read_b128 v[124:127], v255 offset:51200
	ds_read_b128 v[132:135], v255 offset:53248
	ds_read_b128 v[136:139], v255 offset:55296
	ds_read_b128 v[52:55], v253 offset:18432
	ds_read_b128 v[56:59], v253 offset:20480
	ds_read_b128 v[64:67], v253 offset:22528
	s_waitcnt lgkmcnt(14)
	v_mfma_f32_16x16x32_bf16 v[92:95], v[32:35], v[104:107], v[92:95]
	s_waitcnt lgkmcnt(13)
	v_mfma_f32_16x16x32_bf16 v[88:91], v[32:35], v[108:111], v[88:91]
	s_waitcnt lgkmcnt(12)
	v_mfma_f32_16x16x32_bf16 v[84:87], v[32:35], v[112:115], v[84:87]
	s_waitcnt lgkmcnt(11)
	v_mfma_f32_16x16x32_bf16 v[80:83], v[32:35], v[116:119], v[80:83]
	s_waitcnt lgkmcnt(10)
	v_mfma_f32_16x16x32_bf16 v[76:79], v[36:39], v[104:107], v[76:79]
	v_mfma_f32_16x16x32_bf16 v[72:75], v[36:39], v[108:111], v[72:75]
	v_mfma_f32_16x16x32_bf16 v[68:71], v[36:39], v[112:115], v[68:71]
	v_mfma_f32_16x16x32_bf16 v[60:63], v[36:39], v[116:119], v[60:63]
	s_waitcnt lgkmcnt(0)
	s_barrier
	v_mfma_f32_16x16x32_bf16 v[28:31], v[40:43], v[104:107], v[28:31]
	v_mfma_f32_16x16x32_bf16 v[20:23], v[40:43], v[108:111], v[20:23]
	v_mfma_f32_16x16x32_bf16 v[4:7], v[40:43], v[112:115], v[4:7]
	v_mfma_f32_16x16x32_bf16 v[12:15], v[40:43], v[116:119], v[12:15]
	v_mfma_f32_16x16x32_bf16 v[0:3], v[44:47], v[104:107], v[0:3]
	v_mfma_f32_16x16x32_bf16 v[24:27], v[44:47], v[108:111], v[24:27]
	v_mfma_f32_16x16x32_bf16 v[16:19], v[44:47], v[112:115], v[16:19]
	v_mfma_f32_16x16x32_bf16 v[8:11], v[44:47], v[116:119], v[8:11]
	v_mfma_f32_16x16x32_bf16 v[92:95], v[48:51], v[120:123], v[92:95]
	v_mfma_f32_16x16x32_bf16 v[88:91], v[48:51], v[124:127], v[88:91]
	v_mfma_f32_16x16x32_bf16 v[84:87], v[48:51], v[132:135], v[84:87]
	v_mfma_f32_16x16x32_bf16 v[80:83], v[48:51], v[136:139], v[80:83]
	v_mfma_f32_16x16x32_bf16 v[76:79], v[52:55], v[120:123], v[76:79]
	v_mfma_f32_16x16x32_bf16 v[72:75], v[52:55], v[124:127], v[72:75]
	v_mfma_f32_16x16x32_bf16 v[68:71], v[52:55], v[132:135], v[68:71]
	v_mfma_f32_16x16x32_bf16 v[60:63], v[52:55], v[136:139], v[60:63]
	v_mfma_f32_16x16x32_bf16 v[28:31], v[56:59], v[120:123], v[28:31]
	v_mfma_f32_16x16x32_bf16 v[20:23], v[56:59], v[124:127], v[20:23]
	v_mfma_f32_16x16x32_bf16 v[4:7], v[56:59], v[132:135], v[4:7]
	v_mfma_f32_16x16x32_bf16 v[12:15], v[56:59], v[136:139], v[12:15]
	v_mfma_f32_16x16x32_bf16 v[0:3], v[64:67], v[120:123], v[0:3]
	v_mfma_f32_16x16x32_bf16 v[24:27], v[64:67], v[124:127], v[24:27]
	v_mfma_f32_16x16x32_bf16 v[16:19], v[64:67], v[132:135], v[16:19]
	v_mfma_f32_16x16x32_bf16 v[8:11], v[64:67], v[136:139], v[8:11]
	s_nop 7
	s_nop 1
	s_branch .Lg12_join
.Lg12_light:
	v_readfirstlane_b32 s68, v102
	v_readfirstlane_b32 s69, v103
	v_readfirstlane_b32 s70, v104
	v_readfirstlane_b32 s71, v105
	v_readfirstlane_b32 s4, v247
	s_nop 3
	s_mul_i32 s67, s4, 0x2000
	s_sub_u32 s68, s68, s67
	s_subb_u32 s69, s69, 0
	s_sub_u32 s70, s70, s67
	s_subb_u32 s71, s71, 0
	s_lshl_b32 s4, s4, 12
	s_add_u32 m0, s4, 0x0
	v_mov_b32_e32 v92, 0
	global_load_lds_dwordx4 v236, s[68:69]
	v_mov_b32_e32 v93, 0
	s_add_u32 m0, s4, 0x400
	v_mov_b32_e32 v94, 0
	global_load_lds_dwordx4 v237, s[68:69]
	v_mov_b32_e32 v95, 0
	s_add_u32 m0, s4, 0x800
	v_mov_b32_e32 v88, 0
	global_load_lds_dwordx4 v238, s[68:69]
	v_mov_b32_e32 v89, 0
	s_add_u32 m0, s4, 0xc00
	v_mov_b32_e32 v90, 0
	global_load_lds_dwordx4 v239, s[68:69]
	v_mov_b32_e32 v91, 0
	s_add_u32 m0, s4, 0x8000
	v_mov_b32_e32 v84, 0
	global_load_lds_dwordx4 v236, s[70:71]
	v_mov_b32_e32 v85, 0
	s_add_u32 m0, s4, 0x8400
	v_mov_b32_e32 v86, 0
	global_load_lds_dwordx4 v237, s[70:71]
	v_mov_b32_e32 v87, 0
	s_add_u32 m0, s4, 0x8800
	v_mov_b32_e32 v80, 0
	global_load_lds_dwordx4 v238, s[70:71]
	v_mov_b32_e32 v81, 0
	s_add_u32 m0, s4, 0x8c00
	v_mov_b32_e32 v82, 0
	global_load_lds_dwordx4 v239, s[70:71]
	v_mov_b32_e32 v83, 0
	s_add_u32 s68, s68, 0x80
	s_addc_u32 s69, s69, 0
	s_add_u32 s70, s70, 0x80
	s_addc_u32 s71, s71, 0
	s_add_u32 m0, s4, 0x4000
	v_mov_b32_e32 v76, 0
	global_load_lds_dwordx4 v236, s[68:69]
	v_mov_b32_e32 v77, 0
	s_add_u32 m0, s4, 0x4400
	v_mov_b32_e32 v78, 0
	global_load_lds_dwordx4 v237, s[68:69]
	v_mov_b32_e32 v79, 0
	s_add_u32 m0, s4, 0x4800
	v_mov_b32_e32 v72, 0
	global_load_lds_dwordx4 v238, s[68:69]
	v_mov_b32_e32 v73, 0
	s_add_u32 m0, s4, 0x4c00
	v_mov_b32_e32 v74, 0
	global_load_lds_dwordx4 v239, s[68:69]
	v_mov_b32_e32 v75, 0
	s_add_u32 m0, s4, 0xc000
	v_mov_b32_e32 v68, 0
	global_load_lds_dwordx4 v236, s[70:71]
	v_mov_b32_e32 v69, 0
	s_add_u32 m0, s4, 0xc400
	v_mov_b32_e32 v70, 0
	global_load_lds_dwordx4 v237, s[70:71]
	v_mov_b32_e32 v71, 0
	s_add_u32 m0, s4, 0xc800
	v_mov_b32_e32 v60, 0
	global_load_lds_dwordx4 v238, s[70:71]
	v_mov_b32_e32 v61, 0
	s_add_u32 m0, s4, 0xcc00
	v_mov_b32_e32 v62, 0
	global_load_lds_dwordx4 v239, s[70:71]
	v_mov_b32_e32 v63, 0
	s_add_u32 s68, s68, 0x80
	s_addc_u32 s69, s69, 0
	s_add_u32 s70, s70, 0x80
	s_addc_u32 s71, s71, 0
	v_mov_b32_e32 v28, 0
	v_mov_b32_e32 v29, 0
	v_mov_b32_e32 v30, 0
	v_mov_b32_e32 v31, 0
	v_mov_b32_e32 v20, 0
	v_mov_b32_e32 v21, 0
	v_mov_b32_e32 v22, 0
	v_mov_b32_e32 v23, 0
	v_mov_b32_e32 v4, 0
	v_mov_b32_e32 v5, 0
	v_mov_b32_e32 v6, 0
	v_mov_b32_e32 v7, 0
	v_mov_b32_e32 v12, 0
	v_mov_b32_e32 v13, 0
	v_mov_b32_e32 v14, 0
	v_mov_b32_e32 v15, 0
	v_mov_b32_e32 v0, 0
	v_mov_b32_e32 v1, 0
	v_mov_b32_e32 v2, 0
	v_mov_b32_e32 v3, 0
	v_mov_b32_e32 v24, 0
	v_mov_b32_e32 v25, 0
	v_mov_b32_e32 v26, 0
	v_mov_b32_e32 v27, 0
	v_mov_b32_e32 v16, 0
	v_mov_b32_e32 v17, 0
	v_mov_b32_e32 v18, 0
	v_mov_b32_e32 v19, 0
	v_mov_b32_e32 v8, 0
	v_mov_b32_e32 v9, 0
	v_mov_b32_e32 v10, 0
	v_mov_b32_e32 v11, 0
	s_waitcnt vmcnt(8)
	s_barrier
	ds_read_b128 v[32:35], v252 offset:0
	ds_read_b128 v[104:107], v254 offset:32768
	ds_read_b128 v[108:111], v254 offset:34816
	ds_read_b128 v[112:115], v254 offset:36864
	ds_read_b128 v[116:119], v254 offset:38912
	ds_read_b128 v[36:39], v252 offset:2048
	ds_read_b128 v[40:43], v252 offset:4096
	ds_read_b128 v[44:47], v252 offset:6144
	ds_read_b128 v[48:51], v253 offset:0
	ds_read_b128 v[120:123], v255 offset:32768
	ds_read_b128 v[124:127], v255 offset:34816
	ds_read_b128 v[132:135], v255 offset:36864
	ds_read_b128 v[136:139], v255 offset:38912
	s_waitcnt lgkmcnt(11)
	v_mfma_f32_16x16x32_bf16 v[92:95], v[32:35], v[104:107], v[92:95]
	s_waitcnt lgkmcnt(10)
	v_mfma_f32_16x16x32_bf16 v[88:91], v[32:35], v[108:111], v[88:91]
	s_waitcnt lgkmcnt(9)
	v_mfma_f32_16x16x32_bf16 v[84:87], v[32:35], v[112:115], v[84:87]
	s_waitcnt lgkmcnt(8)
	v_mfma_f32_16x16x32_bf16 v[80:83], v[32:35], v[116:119], v[80:83]
	ds_read_b128 v[52:55], v253 offset:2048
	ds_read_b128 v[56:59], v253 offset:4096
	ds_read_b128 v[64:67], v253 offset:6144
	s_waitcnt lgkmcnt(10)
	v_mfma_f32_16x16x32_bf16 v[76:79], v[36:39], v[104:107], v[76:79]
	v_mfma_f32_16x16x32_bf16 v[72:75], v[36:39], v[108:111], v[72:75]
	v_mfma_f32_16x16x32_bf16 v[68:71], v[36:39], v[112:115], v[68:71]
	v_mfma_f32_16x16x32_bf16 v[60:63], v[36:39], v[116:119], v[60:63]
	s_waitcnt lgkmcnt(0)
	s_barrier
	s_add_u32 m0, s4, 0x0
	v_mfma_f32_16x16x32_bf16 v[28:31], v[40:43], v[104:107], v[28:31]
	global_load_lds_dwordx4 v236, s[68:69]
	s_add_u32 m0, s4, 0x400
	v_mfma_f32_16x16x32_bf16 v[20:23], v[40:43], v[108:111], v[20:23]
	global_load_lds_dwordx4 v237, s[68:69]
	s_add_u32 m0, s4, 0x800
	v_mfma_f32_16x16x32_bf16 v[4:7], v[40:43], v[112:115], v[4:7]
	global_load_lds_dwordx4 v238, s[68:69]
	s_add_u32 m0, s4, 0xc00
	v_mfma_f32_16x16x32_bf16 v[12:15], v[40:43], v[116:119], v[12:15]
	global_load_lds_dwordx4 v239, s[68:69]
	s_add_u32 m0, s4, 0x8000
	v_mfma_f32_16x16x32_bf16 v[0:3], v[44:47], v[104:107], v[0:3]
	global_load_lds_dwordx4 v236, s[70:71]
	s_add_u32 m0, s4, 0x8400
	v_mfma_f32_16x16x32_bf16 v[24:27], v[44:47], v[108:111], v[24:27]
	global_load_lds_dwordx4 v237, s[70:71]
	s_add_u32 m0, s4, 0x8800
	v_mfma_f32_16x16x32_bf16 v[16:19], v[44:47], v[112:115], v[16:19]
	global_load_lds_dwordx4 v238, s[70:71]
	s_add_u32 m0, s4, 0x8c00
	v_mfma_f32_16x16x32_bf16 v[8:11], v[44:47], v[116:119], v[8:11]
	global_load_lds_dwordx4 v239, s[70:71]
	s_add_u32 s68, s68, 0x80
	s_addc_u32 s69, s69, 0
	s_add_u32 s70, s70, 0x80
	s_addc_u32 s71, s71, 0
	s_waitcnt vmcnt(8)
	s_barrier
	ds_read_b128 v[32:35], v252 offset:16384
	ds_read_b128 v[104:107], v254 offset:49152
	ds_read_b128 v[108:111], v254 offset:51200
	ds_read_b128 v[112:115], v254 offset:53248
	ds_read_b128 v[116:119], v254 offset:55296
	ds_read_b128 v[36:39], v252 offset:18432
	ds_read_b128 v[40:43], v252 offset:20480
	ds_read_b128 v[44:47], v252 offset:22528
	v_mfma_f32_16x16x32_bf16 v[92:95], v[48:51], v[120:123], v[92:95]
	v_mfma_f32_16x16x32_bf16 v[88:91], v[48:51], v[124:127], v[88:91]
	v_mfma_f32_16x16x32_bf16 v[84:87], v[48:51], v[132:135], v[84:87]
	v_mfma_f32_16x16x32_bf16 v[80:83], v[48:51], v[136:139], v[80:83]
	v_mfma_f32_16x16x32_bf16 v[76:79], v[52:55], v[120:123], v[76:79]
	v_mfma_f32_16x16x32_bf16 v[72:75], v[52:55], v[124:127], v[72:75]
	v_mfma_f32_16x16x32_bf16 v[68:71], v[52:55], v[132:135], v[68:71]
	v_mfma_f32_16x16x32_bf16 v[60:63], v[52:55], v[136:139], v[60:63]
	v_mfma_f32_16x16x32_bf16 v[28:31], v[56:59], v[120:123], v[28:31]
	v_mfma_f32_16x16x32_bf16 v[20:23], v[56:59], v[124:127], v[20:23]
	v_mfma_f32_16x16x32_bf16 v[4:7], v[56:59], v[132:135], v[4:7]
	v_mfma_f32_16x16x32_bf16 v[12:15], v[56:59], v[136:139], v[12:15]
	v_mfma_f32_16x16x32_bf16 v[0:3], v[64:67], v[120:123], v[0:3]
	v_mfma_f32_16x16x32_bf16 v[24:27], v[64:67], v[124:127], v[24:27]
	v_mfma_f32_16x16x32_bf16 v[16:19], v[64:67], v[132:135], v[16:19]
	v_mfma_f32_16x16x32_bf16 v[8:11], v[64:67], v[136:139], v[8:11]
	ds_read_b128 v[48:51], v253 offset:16384
	ds_read_b128 v[120:123], v255 offset:49152
	ds_read_b128 v[124:127], v255 offset:51200
	ds_read_b128 v[132:135], v255 offset:53248
	ds_read_b128 v[136:139], v255 offset:55296
	ds_read_b128 v[52:55], v253 offset:18432
	ds_read_b128 v[56:59], v253 offset:20480
	ds_read_b128 v[64:67], v253 offset:22528
	s_waitcnt lgkmcnt(14)
	v_mfma_f32_16x16x32_bf16 v[92:95], v[32:35], v[104:107], v[92:95]
	s_waitcnt lgkmcnt(13)
	v_mfma_f32_16x16x32_bf16 v[88:91], v[32:35], v[108:111], v[88:91]
	s_waitcnt lgkmcnt(12)
	v_mfma_f32_16x16x32_bf16 v[84:87], v[32:35], v[112:115], v[84:87]
	s_waitcnt lgkmcnt(11)
	v_mfma_f32_16x16x32_bf16 v[80:83], v[32:35], v[116:119], v[80:83]
	s_waitcnt lgkmcnt(10)
	v_mfma_f32_16x16x32_bf16 v[76:79], v[36:39], v[104:107], v[76:79]
	v_mfma_f32_16x16x32_bf16 v[72:75], v[36:39], v[108:111], v[72:75]
	v_mfma_f32_16x16x32_bf16 v[68:71], v[36:39], v[112:115], v[68:71]
	v_mfma_f32_16x16x32_bf16 v[60:63], v[36:39], v[116:119], v[60:63]
	s_waitcnt lgkmcnt(0)
	s_barrier
	s_add_u32 m0, s4, 0x4000
	v_mfma_f32_16x16x32_bf16 v[28:31], v[40:43], v[104:107], v[28:31]
	global_load_lds_dwordx4 v236, s[68:69]
	s_add_u32 m0, s4, 0x4400
	v_mfma_f32_16x16x32_bf16 v[20:23], v[40:43], v[108:111], v[20:23]
	global_load_lds_dwordx4 v237, s[68:69]
	s_add_u32 m0, s4, 0x4800
	v_mfma_f32_16x16x32_bf16 v[4:7], v[40:43], v[112:115], v[4:7]
	global_load_lds_dwordx4 v238, s[68:69]
	s_add_u32 m0, s4, 0x4c00
	v_mfma_f32_16x16x32_bf16 v[12:15], v[40:43], v[116:119], v[12:15]
	global_load_lds_dwordx4 v239, s[68:69]
	s_add_u32 m0, s4, 0xc000
	v_mfma_f32_16x16x32_bf16 v[0:3], v[44:47], v[104:107], v[0:3]
	global_load_lds_dwordx4 v236, s[70:71]
	s_add_u32 m0, s4, 0xc400
	v_mfma_f32_16x16x32_bf16 v[24:27], v[44:47], v[108:111], v[24:27]
	global_load_lds_dwordx4 v237, s[70:71]
	s_add_u32 m0, s4, 0xc800
	v_mfma_f32_16x16x32_bf16 v[16:19], v[44:47], v[112:115], v[16:19]
	global_load_lds_dwordx4 v238, s[70:71]
	s_add_u32 m0, s4, 0xcc00
	v_mfma_f32_16x16x32_bf16 v[8:11], v[44:47], v[116:119], v[8:11]
	global_load_lds_dwordx4 v239, s[70:71]
	s_add_u32 s68, s68, 0x80
	s_addc_u32 s69, s69, 0
	s_add_u32 s70, s70, 0x80
	s_addc_u32 s71, s71, 0
	s_mov_b32 s32, 2
.Lg12l_loop:
	s_waitcnt vmcnt(8)
	s_barrier
	ds_read_b128 v[32:35], v252 offset:0
	ds_read_b128 v[104:107], v254 offset:32768
	ds_read_b128 v[108:111], v254 offset:34816
	ds_read_b128 v[112:115], v254 offset:36864
	ds_read_b128 v[116:119], v254 offset:38912
	ds_read_b128 v[36:39], v252 offset:2048
	ds_read_b128 v[40:43], v252 offset:4096
	ds_read_b128 v[44:47], v252 offset:6144
	v_mfma_f32_16x16x32_bf16 v[92:95], v[48:51], v[120:123], v[92:95]
	v_mfma_f32_16x16x32_bf16 v[88:91], v[48:51], v[124:127], v[88:91]
	v_mfma_f32_16x16x32_bf16 v[84:87], v[48:51], v[132:135], v[84:87]
	v_mfma_f32_16x16x32_bf16 v[80:83], v[48:51], v[136:139], v[80:83]
	v_mfma_f32_16x16x32_bf16 v[76:79], v[52:55], v[120:123], v[76:79]
	v_mfma_f32_16x16x32_bf16 v[72:75], v[52:55], v[124:127], v[72:75]
	v_mfma_f32_16x16x32_bf16 v[68:71], v[52:55], v[132:135], v[68:71]
	v_mfma_f32_16x16x32_bf16 v[60:63], v[52:55], v[136:139], v[60:63]
	v_mfma_f32_16x16x32_bf16 v[28:31], v[56:59], v[120:123], v[28:31]
	v_mfma_f32_16x16x32_bf16 v[20:23], v[56:59], v[124:127], v[20:23]
	v_mfma_f32_16x16x32_bf16 v[4:7], v[56:59], v[132:135], v[4:7]
	v_mfma_f32_16x16x32_bf16 v[12:15], v[56:59], v[136:139], v[12:15]
	v_mfma_f32_16x16x32_bf16 v[0:3], v[64:67], v[120:123], v[0:3]
	v_mfma_f32_16x16x32_bf16 v[24:27], v[64:67], v[124:127], v[24:27]
	v_mfma_f32_16x16x32_bf16 v[16:19], v[64:67], v[132:135], v[16:19]
	v_mfma_f32_16x16x32_bf16 v[8:11], v[64:67], v[136:139], v[8:11]
	ds_read_b128 v[48:51], v253 offset:0
	ds_read_b128 v[120:123], v255 offset:32768
	ds_read_b128 v[124:127], v255 offset:34816
	ds_read_b128 v[132:135], v255 offset:36864
	ds_read_b128 v[136:139], v255 offset:38912
	ds_read_b128 v[52:55], v253 offset:2048
	ds_read_b128 v[56:59], v253 offset:4096
	ds_read_b128 v[64:67], v253 offset:6144
	s_waitcnt lgkmcnt(14)
	v_mfma_f32_16x16x32_bf16 v[92:95], v[32:35], v[104:107], v[92:95]
	s_waitcnt lgkmcnt(13)
	v_mfma_f32_16x16x32_bf16 v[88:91], v[32:35], v[108:111], v[88:91]
	s_waitcnt lgkmcnt(12)
	v_mfma_f32_16x16x32_bf16 v[84:87], v[32:35], v[112:115], v[84:87]
	s_waitcnt lgkmcnt(11)
	v_mfma_f32_16x16x32_bf16 v[80:83], v[32:35], v[116:119], v[80:83]
	s_waitcnt lgkmcnt(10)
	v_mfma_f32_16x16x32_bf16 v[76:79], v[36:39], v[104:107], v[76:79]
	v_mfma_f32_16x16x32_bf16 v[72:75], v[36:39], v[108:111], v[72:75]
	v_mfma_f32_16x16x32_bf16 v[68:71], v[36:39], v[112:115], v[68:71]
	v_mfma_f32_16x16x32_bf16 v[60:63], v[36:39], v[116:119], v[60:63]
	s_waitcnt lgkmcnt(0)
	s_barrier
	s_add_u32 m0, s4, 0x0
	v_mfma_f32_16x16x32_bf16 v[28:31], v[40:43], v[104:107], v[28:31]
	global_load_lds_dwordx4 v236, s[68:69]
	s_add_u32 m0, s4, 0x400
	v_mfma_f32_16x16x32_bf16 v[20:23], v[40:43], v[108:111], v[20:23]
	global_load_lds_dwordx4 v237, s[68:69]
	s_add_u32 m0, s4, 0x800
	v_mfma_f32_16x16x32_bf16 v[4:7], v[40:43], v[112:115], v[4:7]
	global_load_lds_dwordx4 v238, s[68:69]
	s_add_u32 m0, s4, 0xc00
	v_mfma_f32_16x16x32_bf16 v[12:15], v[40:43], v[116:119], v[12:15]
	global_load_lds_dwordx4 v239, s[68:69]
	s_add_u32 m0, s4, 0x8000
	v_mfma_f32_16x16x32_bf16 v[0:3], v[44:47], v[104:107], v[0:3]
	global_load_lds_dwordx4 v236, s[70:71]
	s_add_u32 m0, s4, 0x8400
	v_mfma_f32_16x16x32_bf16 v[24:27], v[44:47], v[108:111], v[24:27]
	global_load_lds_dwordx4 v237, s[70:71]
	s_add_u32 m0, s4, 0x8800
	v_mfma_f32_16x16x32_bf16 v[16:19], v[44:47], v[112:115], v[16:19]
	global_load_lds_dwordx4 v238, s[70:71]
	s_add_u32 m0, s4, 0x8c00
	v_mfma_f32_16x16x32_bf16 v[8:11], v[44:47], v[116:119], v[8:11]
	global_load_lds_dwordx4 v239, s[70:71]
	s_add_u32 s68, s68, 0x80
	s_addc_u32 s69, s69, 0
	s_add_u32 s70, s70, 0x80
	s_addc_u32 s71, s71, 0
	s_waitcnt vmcnt(8)
	s_barrier
	ds_read_b128 v[32:35], v252 offset:16384
	ds_read_b128 v[104:107], v254 offset:49152
	ds_read_b128 v[108:111], v254 offset:51200
	ds_read_b128 v[112:115], v254 offset:53248
	ds_read_b128 v[116:119], v254 offset:55296
	ds_read_b128 v[36:39], v252 offset:18432
	ds_read_b128 v[40:43], v252 offset:20480
	ds_read_b128 v[44:47], v252 offset:22528
	v_mfma_f32_16x16x32_bf16 v[92:95], v[48:51], v[120:123], v[92:95]
	v_mfma_f32_16x16x32_bf16 v[88:91], v[48:51], v[124:127], v[88:91]
	v_mfma_f32_16x16x32_bf16 v[84:87], v[48:51], v[132:135], v[84:87]
	v_mfma_f32_16x16x32_bf16 v[80:83], v[48:51], v[136:139], v[80:83]
	v_mfma_f32_16x16x32_bf16 v[76:79], v[52:55], v[120:123], v[76:79]
	v_mfma_f32_16x16x32_bf16 v[72:75], v[52:55], v[124:127], v[72:75]
	v_mfma_f32_16x16x32_bf16 v[68:71], v[52:55], v[132:135], v[68:71]
	v_mfma_f32_16x16x32_bf16 v[60:63], v[52:55], v[136:139], v[60:63]
	v_mfma_f32_16x16x32_bf16 v[28:31], v[56:59], v[120:123], v[28:31]
	v_mfma_f32_16x16x32_bf16 v[20:23], v[56:59], v[124:127], v[20:23]
	v_mfma_f32_16x16x32_bf16 v[4:7], v[56:59], v[132:135], v[4:7]
	v_mfma_f32_16x16x32_bf16 v[12:15], v[56:59], v[136:139], v[12:15]
	v_mfma_f32_16x16x32_bf16 v[0:3], v[64:67], v[120:123], v[0:3]
	v_mfma_f32_16x16x32_bf16 v[24:27], v[64:67], v[124:127], v[24:27]
	v_mfma_f32_16x16x32_bf16 v[16:19], v[64:67], v[132:135], v[16:19]
	v_mfma_f32_16x16x32_bf16 v[8:11], v[64:67], v[136:139], v[8:11]
	ds_read_b128 v[48:51], v253 offset:16384
	ds_read_b128 v[120:123], v255 offset:49152
	ds_read_b128 v[124:127], v255 offset:51200
	ds_read_b128 v[132:135], v255 offset:53248
	ds_read_b128 v[136:139], v255 offset:55296
	ds_read_b128 v[52:55], v253 offset:18432
	ds_read_b128 v[56:59], v253 offset:20480
	ds_read_b128 v[64:67], v253 offset:22528
	s_waitcnt lgkmcnt(14)
	v_mfma_f32_16x16x32_bf16 v[92:95], v[32:35], v[104:107], v[92:95]
	s_waitcnt lgkmcnt(13)
	v_mfma_f32_16x16x32_bf16 v[88:91], v[32:35], v[108:111], v[88:91]
	s_waitcnt lgkmcnt(12)
	v_mfma_f32_16x16x32_bf16 v[84:87], v[32:35], v[112:115], v[84:87]
	s_waitcnt lgkmcnt(11)
	v_mfma_f32_16x16x32_bf16 v[80:83], v[32:35], v[116:119], v[80:83]
	s_waitcnt lgkmcnt(10)
	v_mfma_f32_16x16x32_bf16 v[76:79], v[36:39], v[104:107], v[76:79]
	v_mfma_f32_16x16x32_bf16 v[72:75], v[36:39], v[108:111], v[72:75]
	v_mfma_f32_16x16x32_bf16 v[68:71], v[36:39], v[112:115], v[68:71]
	v_mfma_f32_16x16x32_bf16 v[60:63], v[36:39], v[116:119], v[60:63]
	s_waitcnt lgkmcnt(0)
	s_barrier
	s_add_u32 m0, s4, 0x4000
	v_mfma_f32_16x16x32_bf16 v[28:31], v[40:43], v[104:107], v[28:31]
	global_load_lds_dwordx4 v236, s[68:69]
	s_add_u32 m0, s4, 0x4400
	v_mfma_f32_16x16x32_bf16 v[20:23], v[40:43], v[108:111], v[20:23]
	global_load_lds_dwordx4 v237, s[68:69]
	s_add_u32 m0, s4, 0x4800
	v_mfma_f32_16x16x32_bf16 v[4:7], v[40:43], v[112:115], v[4:7]
	global_load_lds_dwordx4 v238, s[68:69]
	s_add_u32 m0, s4, 0x4c00
	v_mfma_f32_16x16x32_bf16 v[12:15], v[40:43], v[116:119], v[12:15]
	global_load_lds_dwordx4 v239, s[68:69]
	s_add_u32 m0, s4, 0xc000
	v_mfma_f32_16x16x32_bf16 v[0:3], v[44:47], v[104:107], v[0:3]
	global_load_lds_dwordx4 v236, s[70:71]
	s_add_u32 m0, s4, 0xc400
	v_mfma_f32_16x16x32_bf16 v[24:27], v[44:47], v[108:111], v[24:27]
	global_load_lds_dwordx4 v237, s[70:71]
	s_add_u32 m0, s4, 0xc800
	v_mfma_f32_16x16x32_bf16 v[16:19], v[44:47], v[112:115], v[16:19]
	global_load_lds_dwordx4 v238, s[70:71]
	s_add_u32 m0, s4, 0xcc00
	v_mfma_f32_16x16x32_bf16 v[8:11], v[44:47], v[116:119], v[8:11]
	global_load_lds_dwordx4 v239, s[70:71]
	s_add_u32 s68, s68, 0x80
	s_addc_u32 s69, s69, 0
	s_add_u32 s70, s70, 0x80
	s_addc_u32 s71, s71, 0
	s_sub_u32 s32, s32, 1
	s_cmp_lg_u32 s32, 0
	s_cbranch_scc1 .Lg12l_loop
	s_waitcnt vmcnt(8)
	s_barrier
	ds_read_b128 v[32:35], v252 offset:0
	ds_read_b128 v[104:107], v254 offset:32768
	ds_read_b128 v[108:111], v254 offset:34816
	ds_read_b128 v[112:115], v254 offset:36864
	ds_read_b128 v[116:119], v254 offset:38912
	ds_read_b128 v[36:39], v252 offset:2048
	ds_read_b128 v[40:43], v252 offset:4096
	ds_read_b128 v[44:47], v252 offset:6144
	v_mfma_f32_16x16x32_bf16 v[92:95], v[48:51], v[120:123], v[92:95]
	v_mfma_f32_16x16x32_bf16 v[88:91], v[48:51], v[124:127], v[88:91]
	v_mfma_f32_16x16x32_bf16 v[84:87], v[48:51], v[132:135], v[84:87]
	v_mfma_f32_16x16x32_bf16 v[80:83], v[48:51], v[136:139], v[80:83]
	v_mfma_f32_16x16x32_bf16 v[76:79], v[52:55], v[120:123], v[76:79]
	v_mfma_f32_16x16x32_bf16 v[72:75], v[52:55], v[124:127], v[72:75]
	v_mfma_f32_16x16x32_bf16 v[68:71], v[52:55], v[132:135], v[68:71]
	v_mfma_f32_16x16x32_bf16 v[60:63], v[52:55], v[136:139], v[60:63]
	v_mfma_f32_16x16x32_bf16 v[28:31], v[56:59], v[120:123], v[28:31]
	v_mfma_f32_16x16x32_bf16 v[20:23], v[56:59], v[124:127], v[20:23]
	v_mfma_f32_16x16x32_bf16 v[4:7], v[56:59], v[132:135], v[4:7]
	v_mfma_f32_16x16x32_bf16 v[12:15], v[56:59], v[136:139], v[12:15]
	v_mfma_f32_16x16x32_bf16 v[0:3], v[64:67], v[120:123], v[0:3]
	v_mfma_f32_16x16x32_bf16 v[24:27], v[64:67], v[124:127], v[24:27]
	v_mfma_f32_16x16x32_bf16 v[16:19], v[64:67], v[132:135], v[16:19]
	v_mfma_f32_16x16x32_bf16 v[8:11], v[64:67], v[136:139], v[8:11]
	ds_read_b128 v[48:51], v253 offset:0
	ds_read_b128 v[120:123], v255 offset:32768
	ds_read_b128 v[124:127], v255 offset:34816
	ds_read_b128 v[132:135], v255 offset:36864
	ds_read_b128 v[136:139], v255 offset:38912
	ds_read_b128 v[52:55], v253 offset:2048
	ds_read_b128 v[56:59], v253 offset:4096
	ds_read_b128 v[64:67], v253 offset:6144
	s_waitcnt lgkmcnt(14)
	v_mfma_f32_16x16x32_bf16 v[92:95], v[32:35], v[104:107], v[92:95]
	s_waitcnt lgkmcnt(13)
	v_mfma_f32_16x16x32_bf16 v[88:91], v[32:35], v[108:111], v[88:91]
	s_waitcnt lgkmcnt(12)
	v_mfma_f32_16x16x32_bf16 v[84:87], v[32:35], v[112:115], v[84:87]
	s_waitcnt lgkmcnt(11)
	v_mfma_f32_16x16x32_bf16 v[80:83], v[32:35], v[116:119], v[80:83]
	s_waitcnt lgkmcnt(10)
	v_mfma_f32_16x16x32_bf16 v[76:79], v[36:39], v[104:107], v[76:79]
	v_mfma_f32_16x16x32_bf16 v[72:75], v[36:39], v[108:111], v[72:75]
	v_mfma_f32_16x16x32_bf16 v[68:71], v[36:39], v[112:115], v[68:71]
	v_mfma_f32_16x16x32_bf16 v[60:63], v[36:39], v[116:119], v[60:63]
	s_waitcnt lgkmcnt(0)
	s_barrier
	v_mfma_f32_16x16x32_bf16 v[28:31], v[40:43], v[104:107], v[28:31]
	v_mfma_f32_16x16x32_bf16 v[20:23], v[40:43], v[108:111], v[20:23]
	v_mfma_f32_16x16x32_bf16 v[4:7], v[40:43], v[112:115], v[4:7]
	v_mfma_f32_16x16x32_bf16 v[12:15], v[40:43], v[116:119], v[12:15]
	v_mfma_f32_16x16x32_bf16 v[0:3], v[44:47], v[104:107], v[0:3]
	v_mfma_f32_16x16x32_bf16 v[24:27], v[44:47], v[108:111], v[24:27]
	v_mfma_f32_16x16x32_bf16 v[16:19], v[44:47], v[112:115], v[16:19]
	v_mfma_f32_16x16x32_bf16 v[8:11], v[44:47], v[116:119], v[8:11]
	s_waitcnt vmcnt(0)
	s_barrier
	ds_read_b128 v[32:35], v252 offset:16384
	ds_read_b128 v[104:107], v254 offset:49152
	ds_read_b128 v[108:111], v254 offset:51200
	ds_read_b128 v[112:115], v254 offset:53248
	ds_read_b128 v[116:119], v254 offset:55296
	ds_read_b128 v[36:39], v252 offset:18432
	ds_read_b128 v[40:43], v252 offset:20480
	ds_read_b128 v[44:47], v252 offset:22528
	v_mfma_f32_16x16x32_bf16 v[92:95], v[48:51], v[120:123], v[92:95]
	v_mfma_f32_16x16x32_bf16 v[88:91], v[48:51], v[124:127], v[88:91]
	v_mfma_f32_16x16x32_bf16 v[84:87], v[48:51], v[132:135], v[84:87]
	v_mfma_f32_16x16x32_bf16 v[80:83], v[48:51], v[136:139], v[80:83]
	v_mfma_f32_16x16x32_bf16 v[76:79], v[52:55], v[120:123], v[76:79]
	v_mfma_f32_16x16x32_bf16 v[72:75], v[52:55], v[124:127], v[72:75]
	v_mfma_f32_16x16x32_bf16 v[68:71], v[52:55], v[132:135], v[68:71]
	v_mfma_f32_16x16x32_bf16 v[60:63], v[52:55], v[136:139], v[60:63]
	v_mfma_f32_16x16x32_bf16 v[28:31], v[56:59], v[120:123], v[28:31]
	v_mfma_f32_16x16x32_bf16 v[20:23], v[56:59], v[124:127], v[20:23]
	v_mfma_f32_16x16x32_bf16 v[4:7], v[56:59], v[132:135], v[4:7]
	v_mfma_f32_16x16x32_bf16 v[12:15], v[56:59], v[136:139], v[12:15]
	v_mfma_f32_16x16x32_bf16 v[0:3], v[64:67], v[120:123], v[0:3]
	v_mfma_f32_16x16x32_bf16 v[24:27], v[64:67], v[124:127], v[24:27]
	v_mfma_f32_16x16x32_bf16 v[16:19], v[64:67], v[132:135], v[16:19]
	v_mfma_f32_16x16x32_bf16 v[8:11], v[64:67], v[136:139], v[8:11]
	ds_read_b128 v[48:51], v253 offset:16384
	ds_read_b128 v[120:123], v255 offset:49152
	ds_read_b128 v[124:127], v255 offset:51200
	ds_read_b128 v[132:135], v255 offset:53248
	ds_read_b128 v[136:139], v255 offset:55296
	ds_read_b128 v[52:55], v253 offset:18432
	ds_read_b128 v[56:59], v253 offset:20480
	ds_read_b128 v[64:67], v253 offset:22528
	s_waitcnt lgkmcnt(14)
	v_mfma_f32_16x16x32_bf16 v[92:95], v[32:35], v[104:107], v[92:95]
	s_waitcnt lgkmcnt(13)
	v_mfma_f32_16x16x32_bf16 v[88:91], v[32:35], v[108:111], v[88:91]
	s_waitcnt lgkmcnt(12)
	v_mfma_f32_16x16x32_bf16 v[84:87], v[32:35], v[112:115], v[84:87]
	s_waitcnt lgkmcnt(11)
	v_mfma_f32_16x16x32_bf16 v[80:83], v[32:35], v[116:119], v[80:83]
	s_waitcnt lgkmcnt(10)
	v_mfma_f32_16x16x32_bf16 v[76:79], v[36:39], v[104:107], v[76:79]
	v_mfma_f32_16x16x32_bf16 v[72:75], v[36:39], v[108:111], v[72:75]
	v_mfma_f32_16x16x32_bf16 v[68:71], v[36:39], v[112:115], v[68:71]
	v_mfma_f32_16x16x32_bf16 v[60:63], v[36:39], v[116:119], v[60:63]
	s_waitcnt lgkmcnt(0)
	s_barrier
	v_mfma_f32_16x16x32_bf16 v[28:31], v[40:43], v[104:107], v[28:31]
	v_mfma_f32_16x16x32_bf16 v[20:23], v[40:43], v[108:111], v[20:23]
	v_mfma_f32_16x16x32_bf16 v[4:7], v[40:43], v[112:115], v[4:7]
	v_mfma_f32_16x16x32_bf16 v[12:15], v[40:43], v[116:119], v[12:15]
	v_mfma_f32_16x16x32_bf16 v[0:3], v[44:47], v[104:107], v[0:3]
	v_mfma_f32_16x16x32_bf16 v[24:27], v[44:47], v[108:111], v[24:27]
	v_mfma_f32_16x16x32_bf16 v[16:19], v[44:47], v[112:115], v[16:19]
	v_mfma_f32_16x16x32_bf16 v[8:11], v[44:47], v[116:119], v[8:11]
	v_mfma_f32_16x16x32_bf16 v[92:95], v[48:51], v[120:123], v[92:95]
	v_mfma_f32_16x16x32_bf16 v[88:91], v[48:51], v[124:127], v[88:91]
	v_mfma_f32_16x16x32_bf16 v[84:87], v[48:51], v[132:135], v[84:87]
	v_mfma_f32_16x16x32_bf16 v[80:83], v[48:51], v[136:139], v[80:83]
	v_mfma_f32_16x16x32_bf16 v[76:79], v[52:55], v[120:123], v[76:79]
	v_mfma_f32_16x16x32_bf16 v[72:75], v[52:55], v[124:127], v[72:75]
	v_mfma_f32_16x16x32_bf16 v[68:71], v[52:55], v[132:135], v[68:71]
	v_mfma_f32_16x16x32_bf16 v[60:63], v[52:55], v[136:139], v[60:63]
	v_mfma_f32_16x16x32_bf16 v[28:31], v[56:59], v[120:123], v[28:31]
	v_mfma_f32_16x16x32_bf16 v[20:23], v[56:59], v[124:127], v[20:23]
	v_mfma_f32_16x16x32_bf16 v[4:7], v[56:59], v[132:135], v[4:7]
	v_mfma_f32_16x16x32_bf16 v[12:15], v[56:59], v[136:139], v[12:15]
	v_mfma_f32_16x16x32_bf16 v[0:3], v[64:67], v[120:123], v[0:3]
	v_mfma_f32_16x16x32_bf16 v[24:27], v[64:67], v[124:127], v[24:27]
	v_mfma_f32_16x16x32_bf16 v[16:19], v[64:67], v[132:135], v[16:19]
	v_mfma_f32_16x16x32_bf16 v[8:11], v[64:67], v[136:139], v[8:11]
	s_nop 7
	s_nop 1
.Lg12_join:
	v_add_u32_e32 v32, s66, v141
	v_lshl_or_b32 v96, s65, 8, v142
	v_ashrrev_i32_e32 v33, 31, v32
	v_lshl_add_u64 v[34:35], v[98:99], 0, v[96:97]
	v_lshlrev_b64 v[32:33], 11, v[32:33]
	v_cvt_pk_bf16_f32 v36, v92, s0
	v_lshl_add_u64 v[32:33], v[34:35], 0, v[32:33]
	global_store_short v[32:33], v36, off
	v_add_co_u32_e32 v36, vcc, 0x1000, v32
	v_cvt_pk_bf16_f32 v38, v94, s0
	s_nop 0
	v_addc_co_u32_e32 v37, vcc, 0, v33, vcc
	v_cvt_pk_bf16_f32 v40, v95, s0
	global_store_short v[36:37], v38, off
	global_store_short v[36:37], v40, off offset:2048
	v_cvt_pk_bf16_f32 v36, v88, s0
	v_cvt_pk_bf16_f32 v34, v93, s0
	global_store_short v[32:33], v36, off offset:32
	v_cvt_pk_bf16_f32 v36, v89, s0
	global_store_short v[32:33], v34, off offset:2048
	v_lshl_add_u64 v[34:35], v[32:33], 0, s[8:9]
	global_store_short v[32:33], v36, off offset:2080
	v_cvt_pk_bf16_f32 v36, v90, s0
	v_lshl_add_u64 v[38:39], v[32:33], 0, s[10:11]
	global_store_short v[34:35], v36, off offset:32
	v_cvt_pk_bf16_f32 v36, v91, s0
	global_store_short v[38:39], v36, off offset:32
	v_cvt_pk_bf16_f32 v36, v84, s0
	global_store_short v[32:33], v36, off offset:64
	v_cvt_pk_bf16_f32 v36, v85, s0
	global_store_short v[32:33], v36, off offset:2112
	v_cvt_pk_bf16_f32 v36, v86, s0
	global_store_short v[34:35], v36, off offset:64
	v_cvt_pk_bf16_f32 v36, v87, s0
	global_store_short v[38:39], v36, off offset:64
	v_cvt_pk_bf16_f32 v36, v80, s0
	global_store_short v[32:33], v36, off offset:96
	v_cvt_pk_bf16_f32 v36, v81, s0
	global_store_short v[32:33], v36, off offset:2144
	v_cvt_pk_bf16_f32 v36, v82, s0
	global_store_short v[34:35], v36, off offset:96
	v_add_co_u32_e32 v36, vcc, s51, v32
	v_cvt_pk_bf16_f32 v34, v83, s0
	s_nop 0
	v_addc_co_u32_e32 v37, vcc, 0, v33, vcc
	global_store_short v[38:39], v34, off offset:96
	v_add_co_u32_e32 v38, vcc, s54, v32
	v_cvt_pk_bf16_f32 v42, v77, s0
	v_cvt_pk_bf16_f32 v40, v76, s0
	v_addc_co_u32_e32 v39, vcc, 0, v33, vcc
	global_store_short v[36:37], v42, off offset:2048
	v_cvt_pk_bf16_f32 v42, v78, s0
	s_waitcnt vmcnt(19)
	v_cvt_pk_bf16_f32 v44, v79, s0
	v_lshl_add_u64 v[34:35], v[32:33], 0, s[12:13]
	global_store_short v[38:39], v40, off offset:-4096
	global_store_short v[38:39], v42, off
	global_store_short v[38:39], v44, off offset:2048
	v_cvt_pk_bf16_f32 v38, v72, s0
	v_lshl_add_u64 v[40:41], v[32:33], 0, s[14:15]
	global_store_short v[34:35], v38, off offset:32
	v_cvt_pk_bf16_f32 v38, v73, s0
	v_lshl_add_u64 v[36:37], v[32:33], 0, s[16:17]
	global_store_short v[40:41], v38, off offset:32
	v_cvt_pk_bf16_f32 v38, v74, s0
	v_lshl_add_u64 v[42:43], v[32:33], 0, s[18:19]
	global_store_short v[36:37], v38, off offset:32
	v_cvt_pk_bf16_f32 v38, v75, s0
	global_store_short v[42:43], v38, off offset:32
	v_cvt_pk_bf16_f32 v38, v68, s0
	global_store_short v[34:35], v38, off offset:64
	v_cvt_pk_bf16_f32 v38, v69, s0
	global_store_short v[40:41], v38, off offset:64
	v_cvt_pk_bf16_f32 v38, v70, s0
	global_store_short v[36:37], v38, off offset:64
	v_cvt_pk_bf16_f32 v38, v71, s0
	global_store_short v[42:43], v38, off offset:64
	v_cvt_pk_bf16_f32 v38, v60, s0
	global_store_short v[34:35], v38, off offset:96
	v_cvt_pk_bf16_f32 v34, v61, s0
	global_store_short v[40:41], v34, off offset:96
	v_cvt_pk_bf16_f32 v34, v62, s0
	global_store_short v[36:37], v34, off offset:96
	v_add_co_u32_e32 v36, vcc, s55, v32
	v_cvt_pk_bf16_f32 v34, v63, s0
	s_nop 0
	v_addc_co_u32_e32 v37, vcc, 0, v33, vcc
	v_add_co_u32_e32 v38, vcc, s59, v32
	global_store_short v[42:43], v34, off offset:96
	v_cvt_pk_bf16_f32 v28, v28, s0
	v_lshl_add_u64 v[34:35], v[32:33], 0, s[20:21]
	v_addc_co_u32_e32 v39, vcc, 0, v33, vcc
	v_cvt_pk_bf16_f32 v4, v4, s0
	global_store_short v[38:39], v28, off offset:-4096
	v_cvt_pk_bf16_f32 v40, v29, s0
	v_lshl_add_u64 v[28:29], v[32:33], 0, s[22:23]
	global_store_short v[34:35], v4, off offset:64
	v_cvt_pk_bf16_f32 v4, v5, s0
	global_store_short v[36:37], v40, off offset:2048
	v_cvt_pk_bf16_f32 v30, v30, s0
	v_lshl_add_u64 v[36:37], v[32:33], 0, s[24:25]
	global_store_short v[28:29], v4, off offset:64
	v_cvt_pk_bf16_f32 v4, v6, s0
	global_store_short v[38:39], v30, off
	v_cvt_pk_bf16_f32 v40, v31, s0
	v_lshl_add_u64 v[30:31], v[32:33], 0, s[26:27]
	global_store_short v[36:37], v4, off offset:64
	v_cvt_pk_bf16_f32 v4, v7, s0
	global_store_short v[30:31], v4, off offset:64
	v_cvt_pk_bf16_f32 v4, v12, s0
	v_add_co_u32_e32 v6, vcc, s62, v32
	global_store_short v[34:35], v4, off offset:96
	v_cvt_pk_bf16_f32 v4, v13, s0
	v_addc_co_u32_e32 v7, vcc, 0, v33, vcc
	global_store_short v[28:29], v4, off offset:96
	v_cvt_pk_bf16_f32 v4, v14, s0
	v_add_co_u32_e32 v12, vcc, s63, v32
	v_cvt_pk_bf16_f32 v14, v1, s0
	global_store_short v[36:37], v4, off offset:96
	v_cvt_pk_bf16_f32 v4, v15, s0
	v_cvt_pk_bf16_f32 v0, v0, s0
	v_addc_co_u32_e32 v13, vcc, 0, v33, vcc
	global_store_short v[6:7], v14, off offset:2048
	v_cvt_pk_bf16_f32 v2, v2, s0
	v_cvt_pk_bf16_f32 v14, v3, s0
	global_store_short v[30:31], v4, off offset:96
	v_lshl_add_u64 v[4:5], v[32:33], 0, s[28:29]
	global_store_short v[12:13], v0, off offset:-4096
	global_store_short v[12:13], v2, off
	global_store_short v[12:13], v14, off offset:2048
	v_cvt_pk_bf16_f32 v12, v24, s0
	v_lshl_add_u64 v[0:1], v[32:33], 0, s[30:31]
	global_store_short v[4:5], v12, off offset:32
	v_cvt_pk_bf16_f32 v12, v25, s0
	v_lshl_add_u64 v[6:7], v[32:33], 0, s[34:35]
	global_store_short v[0:1], v12, off offset:32
	v_cvt_pk_bf16_f32 v12, v26, s0
	v_lshl_add_u64 v[2:3], v[32:33], 0, s[36:37]
	global_store_short v[6:7], v12, off offset:32
	v_cvt_pk_bf16_f32 v12, v27, s0
	v_cvt_pk_bf16_f32 v20, v20, s0
	global_store_short v[2:3], v12, off offset:32
	v_cvt_pk_bf16_f32 v12, v16, s0
	v_cvt_pk_bf16_f32 v8, v8, s0
	global_store_short v[34:35], v20, off offset:32
	v_cvt_pk_bf16_f32 v20, v21, s0
	global_store_short v[4:5], v12, off offset:64
	v_cvt_pk_bf16_f32 v12, v17, s0
	global_store_short v[4:5], v8, off offset:96
	v_cvt_pk_bf16_f32 v4, v9, s0
	global_store_short v[28:29], v20, off offset:32
	v_cvt_pk_bf16_f32 v20, v22, s0
	global_store_short v[0:1], v12, off offset:64
	v_cvt_pk_bf16_f32 v12, v18, s0
	global_store_short v[0:1], v4, off offset:96
	v_cvt_pk_bf16_f32 v0, v10, s0
	s_add_i32 s64, s64, s2
	global_store_short v[36:37], v20, off offset:32
	v_cvt_pk_bf16_f32 v20, v23, s0
	global_store_short v[6:7], v12, off offset:64
	v_cvt_pk_bf16_f32 v12, v19, s0
	global_store_short v[6:7], v0, off offset:96
	v_cvt_pk_bf16_f32 v0, v11, s0
	s_cmpk_lt_i32 s64, 0x200
	global_store_short v[38:39], v40, off offset:2048
	global_store_short v[30:31], v20, off offset:32
	global_store_short v[2:3], v12, off offset:64
	global_store_short v[2:3], v0, off offset:96
	s_cbranch_scc1 .LBB0_1199

.LBB0_2655:
	s_cmp_gt_i32 s60, 28
	s_cselect_b64 s[2:3], -1, 0
	s_cmp_lt_i32 s61, 28
	s_cselect_b64 s[4:5], -1, 0
	s_or_b64 s[2:3], s[2:3], s[4:5]
	s_and_b64 vcc, exec, s[2:3]
	s_cbranch_vccnz .LBB0_2719
	s_mov_b64 s[4:5], s[0:1]
	s_cmpk_gt_i32 s58, 0x1ff
	s_cbranch_scc1 .LBB0_2665
	s_load_dwordx2 s[4:5], s[4:5], 0xe0
	v_xor_b32_e32 v5, v163, v162
	v_lshlrev_b32_e32 v5, 4, v5
	v_and_b32_e32 v3, 15, v162
	v_lshrrev_b32_e32 v134, 3, v162
	v_and_b32_e32 v5, 0x70, v5
	v_lshrrev_b32_e32 v2, 7, v162
	v_lshl_or_b32 v135, v134, 7, v5
	v_lshlrev_b32_e32 v5, 7, v3
	v_bfe_u32 v4, v162, 4, 2
	v_mov_b32_e32 v97, 0
	v_lshl_or_b32 v7, v2, 13, v5
	v_lshlrev_b32_e32 v2, 6, v2
	v_lshlrev_b32_e32 v96, 1, v3
	v_lshl_or_b32 v140, v4, 2, v2
	s_waitcnt lgkmcnt(0)
	v_lshl_add_u64 v[2:3], s[4:5], 0, v[96:97]
	s_mov_b64 s[2:3], 0x9b7a100
	v_lshl_add_u64 v[98:99], v[2:3], 0, s[2:3]
	s_add_u32 s3, s4, 0x6a80000
	s_addc_u32 s44, s5, 0
	s_add_u32 s45, s4, 0xab7a100
	v_bfe_u32 v6, v162, 1, 3
	s_load_dword s2, s[0:1], 0xf0
	s_addc_u32 s46, s5, 0
	v_bfe_u32 v1, v162, 6, 1
	v_bitop3_b32 v6, v163, v6, 3 bitop3:0x6c
	s_add_u32 s47, s4, 0x6680000
	v_lshlrev_b32_e32 v0, 3, v162
	v_lshl_or_b32 v5, v1, 13, v5
	v_lshlrev_b32_e32 v6, 4, v6
	s_addc_u32 s48, s5, 0
	v_and_b32_e32 v0, 56, v0
	v_or_b32_e32 v136, v7, v6
	v_or_b32_e32 v137, v5, v6
	v_xor_b32_e32 v6, 64, v6
	v_lshlrev_b32_e32 v1, 6, v1
	s_add_u32 s49, s4, 0xbb7a100
	v_or_b32_e32 v138, v7, v6
	v_or_b32_e32 v139, v5, v6
	s_addc_u32 s50, s5, 0
	s_mov_b32 s5, 0
	v_lshlrev_b32_e32 v100, 1, v0
	v_mov_b32_e32 v101, v97
	s_mov_b64 s[6:7], 0x100
	v_lshlrev_b32_e32 v141, 1, v1
	s_mov_b64 s[8:9], 0x1000
	s_mov_b64 s[10:11], 0x1800
	s_mov_b64 s[12:13], 0x8000
	s_mov_b32 s51, 0x8000
	s_mov_b64 s[14:15], 0x8800
	s_mov_b64 s[16:17], 0x9000
	s_mov_b32 s54, 0x9000
	s_mov_b64 s[18:19], 0x9800
	s_mov_b64 s[20:21], 0x10000
	s_mov_b32 s55, 0x10000
	s_mov_b64 s[22:23], 0x10800
	s_mov_b64 s[24:25], 0x11000
	s_mov_b32 s59, 0x11000
	s_mov_b64 s[26:27], 0x11800
	s_mov_b64 s[28:29], 0x18000
	s_mov_b32 s62, 0x18000
	s_mov_b64 s[30:31], 0x18800
	s_mov_b64 s[34:35], 0x19000
	s_mov_b32 s63, 0x19000
	s_mov_b64 s[36:37], 0x19800
	s_mov_b32 s64, s58
	v_and_b32_e32 v240, 63, v162
	v_lshrrev_b32_e32 v247, 6, v162
	v_lshrrev_b32_e32 v242, 3, v240
	v_lshl_add_u32 v242, v247, 5, v242
	v_and_b32_e32 v243, 7, v240
	v_lshrrev_b32_e32 v244, 4, v240
	v_xor_b32_e32 v243, v243, v244
	v_lshlrev_b32_e32 v243, 4, v243
	v_mov_b32_e32 v241, 0x1000
	v_mad_u32_u24 v248, v242, v241, v243
	v_xor_b32_e32 v249, 64, v248
	v_add_u32_e32 v249, 0x8000, v249
	v_add_u32_e32 v250, 0x10000, v248
	v_xor_b32_e32 v251, 64, v248
	v_add_u32_e32 v251, 0x18000, v251
	v_and_b32_e32 v241, 15, v240
	v_lshrrev_b32_e32 v242, 1, v241
	v_xor_b32_e32 v242, v242, v244
	v_lshlrev_b32_e32 v242, 4, v242
	v_lshl_or_b32 v242, v241, 7, v242
	v_lshrrev_b32_e32 v243, 1, v247
	v_lshl_or_b32 v252, v243, 13, v242
	v_xor_b32_e32 v253, 64, v252
	v_and_b32_e32 v243, 1, v247
	v_lshl_or_b32 v254, v243, 13, v242
	v_xor_b32_e32 v255, 64, v254
	v_and_b32_e32 v240, 63, v162
	v_lshrrev_b32_e32 v247, 6, v162
	v_lshrrev_b32_e32 v242, 3, v240
	v_lshl_add_u32 v242, v247, 5, v242
	v_and_b32_e32 v243, 7, v240
	v_lshrrev_b32_e32 v244, 4, v240
	v_xor_b32_e32 v243, v243, v244
	v_lshlrev_b32_e32 v243, 4, v243
	v_mov_b32_e32 v241, 0x400
	v_mad_u32_u24 v236, v242, v241, v243
	v_xor_b32_e32 v237, 64, v236
	v_add_u32_e32 v237, 0x2000, v237
	v_add_u32_e32 v238, 0x4000, v236
	v_xor_b32_e32 v239, 64, v236
	v_add_u32_e32 v239, 0x6000, v239
	v_and_b32_e32 v241, 15, v240
	v_lshrrev_b32_e32 v242, 1, v241
	v_xor_b32_e32 v242, v242, v244
	v_lshlrev_b32_e32 v242, 4, v242
	v_lshl_or_b32 v242, v241, 7, v242
	v_lshrrev_b32_e32 v243, 1, v247
	v_lshl_or_b32 v252, v243, 13, v242
	v_xor_b32_e32 v253, 64, v252
	v_and_b32_e32 v243, 1, v247
	v_lshl_or_b32 v254, v243, 13, v242
	v_xor_b32_e32 v255, 64, v254

.LBB0_2662:
	v_mul_u32_u24_e32 v0, s4, v134
	v_lshlrev_b32_e32 v96, 1, v0
	v_lshl_add_u64 v[0:1], s[38:39], 0, v[96:97]
	v_lshl_add_u64 v[102:103], v[0:1], 0, v[100:101]
	v_lshl_add_u64 v[0:1], s[40:41], 0, v[96:97]
	v_lshl_add_u64 v[104:105], v[0:1], 0, v[100:101]
	s_lshl_b32 s38, s4, 6
	s_mov_b32 s39, s5
	v_lshl_add_u64 v[2:3], v[102:103], 0, s[38:39]
	v_lshl_add_u64 v[6:7], v[104:105], 0, s[38:39]
	v_lshl_add_u64 v[4:5], v[2:3], 0, s[38:39]
	v_lshl_add_u64 v[12:13], v[6:7], 0, s[38:39]
	v_lshl_add_u64 v[88:89], v[4:5], 0, s[38:39]
	v_lshl_add_u64 v[90:91], v[12:13], 0, s[38:39]
	s_lshr_b32 s42, s4, 6
	s_lshl_b32 s40, s4, 5
	s_lshl_b32 s4, s4, 7
	s_add_i32 s67, s42, -1
	s_sub_u32 s68, 0, s4
	s_subb_u32 s69, 0, 0
	v_lshl_add_u64 v[106:107], v[88:89], 0, s[68:69]
	v_lshl_add_u64 v[108:109], v[90:91], 0, s[68:69]
	v_lshl_add_u64 v[110:111], v[106:107], 0, s[38:39]
	v_lshl_add_u64 v[112:113], v[108:109], 0, s[38:39]
	v_mov_b32_e32 v8, 0
	v_lshl_add_u64 v[114:115], v[110:111], 0, s[38:39]
	v_lshl_add_u64 v[116:117], v[112:113], 0, s[38:39]
	s_mov_b32 s43, 0
	s_mov_b32 s41, s5
	v_mov_b32_e32 v9, v8
	v_mov_b32_e32 v10, v8
	v_mov_b32_e32 v11, v8
	v_mov_b32_e32 v16, v8
	v_mov_b32_e32 v17, v8
	v_mov_b32_e32 v18, v8
	v_mov_b32_e32 v19, v8
	v_mov_b32_e32 v24, v8
	v_mov_b32_e32 v25, v8
	v_mov_b32_e32 v26, v8
	v_mov_b32_e32 v27, v8
	v_mov_b32_e32 v0, v8
	v_mov_b32_e32 v1, v8
	v_mov_b32_e32 v2, v8
	v_mov_b32_e32 v3, v8
	v_mov_b32_e32 v12, v8
	v_mov_b32_e32 v13, v8
	v_mov_b32_e32 v14, v8
	v_mov_b32_e32 v15, v8
	v_mov_b32_e32 v4, v8
	v_mov_b32_e32 v5, v8
	v_mov_b32_e32 v6, v8
	v_mov_b32_e32 v7, v8
	s_lshl_b32 s40, s40, 1
	v_lshl_add_u64 v[118:119], v[104:105], 0, s[6:7]
	v_lshl_add_u64 v[120:121], v[102:103], 0, s[6:7]
	v_lshl_add_u64 v[122:123], v[108:109], 0, s[6:7]
	v_lshl_add_u64 v[124:125], v[106:107], 0, s[6:7]
	v_lshl_add_u64 v[126:127], v[112:113], 0, s[6:7]
	v_lshl_add_u64 v[130:131], v[110:111], 0, s[6:7]
	v_lshl_add_u64 v[128:129], v[116:117], 0, s[6:7]
	v_lshl_add_u64 v[132:133], v[114:115], 0, s[6:7]
	v_mov_b32_e32 v88, v8
	v_mov_b32_e32 v89, v8
	v_mov_b32_e32 v90, v8
	v_mov_b32_e32 v91, v8
	v_mov_b32_e32 v92, v8
	v_mov_b32_e32 v93, v8
	v_mov_b32_e32 v94, v8
	v_mov_b32_e32 v95, v8
	v_mov_b32_e32 v20, v8
	v_mov_b32_e32 v21, v8
	v_mov_b32_e32 v22, v8
	v_mov_b32_e32 v23, v8
	v_mov_b32_e32 v28, v8
	v_mov_b32_e32 v29, v8
	v_mov_b32_e32 v30, v8
	v_mov_b32_e32 v31, v8
	v_mov_b32_e32 v60, v8
	v_mov_b32_e32 v61, v8
	v_mov_b32_e32 v62, v8
	v_mov_b32_e32 v63, v8
	v_mov_b32_e32 v68, v8
	v_mov_b32_e32 v69, v8
	v_mov_b32_e32 v70, v8
	v_mov_b32_e32 v71, v8
	v_mov_b32_e32 v72, v8
	v_mov_b32_e32 v73, v8
	v_mov_b32_e32 v74, v8
	v_mov_b32_e32 v75, v8
	v_mov_b32_e32 v76, v8
	v_mov_b32_e32 v77, v8
	v_mov_b32_e32 v78, v8
	v_mov_b32_e32 v79, v8
	v_mov_b32_e32 v80, v8
	v_mov_b32_e32 v81, v8
	v_mov_b32_e32 v82, v8
	v_mov_b32_e32 v83, v8
	v_mov_b32_e32 v84, v8
	v_mov_b32_e32 v85, v8
	v_mov_b32_e32 v86, v8
	v_mov_b32_e32 v87, v8
	s_cmpk_gt_i32 s64, 0xff
	s_cbranch_scc1 .Lg28_light
	v_readfirstlane_b32 s68, v102
	v_readfirstlane_b32 s69, v103
	v_readfirstlane_b32 s70, v104
	v_readfirstlane_b32 s71, v105
	v_readfirstlane_b32 s4, v247
	s_nop 3
	s_mul_i32 s67, s4, 0x8000
	s_sub_u32 s68, s68, s67
	s_subb_u32 s69, s69, 0
	s_sub_u32 s70, s70, s67
	s_subb_u32 s71, s71, 0
	s_lshl_b32 s4, s4, 12
	s_add_u32 m0, s4, 0x0
	v_mov_b32_e32 v92, 0
	global_load_lds_dwordx4 v248, s[68:69]
	v_mov_b32_e32 v93, 0
	s_add_u32 m0, s4, 0x400
	v_mov_b32_e32 v94, 0
	global_load_lds_dwordx4 v249, s[68:69]
	v_mov_b32_e32 v95, 0
	s_add_u32 m0, s4, 0x800
	v_mov_b32_e32 v88, 0
	global_load_lds_dwordx4 v250, s[68:69]
	v_mov_b32_e32 v89, 0
	s_add_u32 m0, s4, 0xc00
	v_mov_b32_e32 v90, 0
	global_load_lds_dwordx4 v251, s[68:69]
	v_mov_b32_e32 v91, 0
	s_add_u32 m0, s4, 0x8000
	v_mov_b32_e32 v84, 0
	global_load_lds_dwordx4 v248, s[70:71]
	v_mov_b32_e32 v85, 0
	s_add_u32 m0, s4, 0x8400
	v_mov_b32_e32 v86, 0
	global_load_lds_dwordx4 v249, s[70:71]
	v_mov_b32_e32 v87, 0
	s_add_u32 m0, s4, 0x8800
	v_mov_b32_e32 v80, 0
	global_load_lds_dwordx4 v250, s[70:71]
	v_mov_b32_e32 v81, 0
	s_add_u32 m0, s4, 0x8c00
	v_mov_b32_e32 v82, 0
	global_load_lds_dwordx4 v251, s[70:71]
	v_mov_b32_e32 v83, 0
	s_add_u32 s68, s68, 0x80
	s_addc_u32 s69, s69, 0
	s_add_u32 s70, s70, 0x80
	s_addc_u32 s71, s71, 0
	s_add_u32 m0, s4, 0x4000
	v_mov_b32_e32 v76, 0
	global_load_lds_dwordx4 v248, s[68:69]
	v_mov_b32_e32 v77, 0
	s_add_u32 m0, s4, 0x4400
	v_mov_b32_e32 v78, 0
	global_load_lds_dwordx4 v249, s[68:69]
	v_mov_b32_e32 v79, 0
	s_add_u32 m0, s4, 0x4800
	v_mov_b32_e32 v72, 0
	global_load_lds_dwordx4 v250, s[68:69]
	v_mov_b32_e32 v73, 0
	s_add_u32 m0, s4, 0x4c00
	v_mov_b32_e32 v74, 0
	global_load_lds_dwordx4 v251, s[68:69]
	v_mov_b32_e32 v75, 0
	s_add_u32 m0, s4, 0xc000
	v_mov_b32_e32 v68, 0
	global_load_lds_dwordx4 v248, s[70:71]
	v_mov_b32_e32 v69, 0
	s_add_u32 m0, s4, 0xc400
	v_mov_b32_e32 v70, 0
	global_load_lds_dwordx4 v249, s[70:71]
	v_mov_b32_e32 v71, 0
	s_add_u32 m0, s4, 0xc800
	v_mov_b32_e32 v60, 0
	global_load_lds_dwordx4 v250, s[70:71]
	v_mov_b32_e32 v61, 0
	s_add_u32 m0, s4, 0xcc00
	v_mov_b32_e32 v62, 0
	global_load_lds_dwordx4 v251, s[70:71]
	v_mov_b32_e32 v63, 0
	s_add_u32 s68, s68, 0x80
	s_addc_u32 s69, s69, 0
	s_add_u32 s70, s70, 0x80
	s_addc_u32 s71, s71, 0
	v_mov_b32_e32 v28, 0
	v_mov_b32_e32 v29, 0
	v_mov_b32_e32 v30, 0
	v_mov_b32_e32 v31, 0
	v_mov_b32_e32 v20, 0
	v_mov_b32_e32 v21, 0
	v_mov_b32_e32 v22, 0
	v_mov_b32_e32 v23, 0
	v_mov_b32_e32 v4, 0
	v_mov_b32_e32 v5, 0
	v_mov_b32_e32 v6, 0
	v_mov_b32_e32 v7, 0
	v_mov_b32_e32 v12, 0
	v_mov_b32_e32 v13, 0
	v_mov_b32_e32 v14, 0
	v_mov_b32_e32 v15, 0
	v_mov_b32_e32 v0, 0
	v_mov_b32_e32 v1, 0
	v_mov_b32_e32 v2, 0
	v_mov_b32_e32 v3, 0
	v_mov_b32_e32 v24, 0
	v_mov_b32_e32 v25, 0
	v_mov_b32_e32 v26, 0
	v_mov_b32_e32 v27, 0
	v_mov_b32_e32 v16, 0
	v_mov_b32_e32 v17, 0
	v_mov_b32_e32 v18, 0
	v_mov_b32_e32 v19, 0
	v_mov_b32_e32 v8, 0
	v_mov_b32_e32 v9, 0
	v_mov_b32_e32 v10, 0
	v_mov_b32_e32 v11, 0
	s_waitcnt vmcnt(8)
	s_barrier
	ds_read_b128 v[32:35], v252 offset:0
	ds_read_b128 v[104:107], v254 offset:32768
	ds_read_b128 v[108:111], v254 offset:34816
	ds_read_b128 v[112:115], v254 offset:36864
	ds_read_b128 v[116:119], v254 offset:38912
	ds_read_b128 v[36:39], v252 offset:2048
	ds_read_b128 v[40:43], v252 offset:4096
	ds_read_b128 v[44:47], v252 offset:6144
	ds_read_b128 v[48:51], v253 offset:0
	ds_read_b128 v[120:123], v255 offset:32768
	ds_read_b128 v[124:127], v255 offset:34816
	ds_read_b128 v[136:139], v255 offset:36864
	ds_read_b128 v[144:147], v255 offset:38912
	s_waitcnt lgkmcnt(11)
	v_mfma_f32_16x16x32_bf16 v[92:95], v[32:35], v[104:107], v[92:95]
	s_waitcnt lgkmcnt(10)
	v_mfma_f32_16x16x32_bf16 v[88:91], v[32:35], v[108:111], v[88:91]
	s_waitcnt lgkmcnt(9)
	v_mfma_f32_16x16x32_bf16 v[84:87], v[32:35], v[112:115], v[84:87]
	s_waitcnt lgkmcnt(8)
	v_mfma_f32_16x16x32_bf16 v[80:83], v[32:35], v[116:119], v[80:83]
	ds_read_b128 v[52:55], v253 offset:2048
	ds_read_b128 v[56:59], v253 offset:4096
	ds_read_b128 v[64:67], v253 offset:6144
	s_waitcnt lgkmcnt(10)
	v_mfma_f32_16x16x32_bf16 v[76:79], v[36:39], v[104:107], v[76:79]
	v_mfma_f32_16x16x32_bf16 v[72:75], v[36:39], v[108:111], v[72:75]
	v_mfma_f32_16x16x32_bf16 v[68:71], v[36:39], v[112:115], v[68:71]
	v_mfma_f32_16x16x32_bf16 v[60:63], v[36:39], v[116:119], v[60:63]
	s_waitcnt lgkmcnt(0)
	s_barrier
	s_add_u32 m0, s4, 0x0
	v_mfma_f32_16x16x32_bf16 v[28:31], v[40:43], v[104:107], v[28:31]
	global_load_lds_dwordx4 v248, s[68:69]
	s_add_u32 m0, s4, 0x400
	v_mfma_f32_16x16x32_bf16 v[20:23], v[40:43], v[108:111], v[20:23]
	global_load_lds_dwordx4 v249, s[68:69]
	s_add_u32 m0, s4, 0x800
	v_mfma_f32_16x16x32_bf16 v[4:7], v[40:43], v[112:115], v[4:7]
	global_load_lds_dwordx4 v250, s[68:69]
	s_add_u32 m0, s4, 0xc00
	v_mfma_f32_16x16x32_bf16 v[12:15], v[40:43], v[116:119], v[12:15]
	global_load_lds_dwordx4 v251, s[68:69]
	s_add_u32 m0, s4, 0x8000
	v_mfma_f32_16x16x32_bf16 v[0:3], v[44:47], v[104:107], v[0:3]
	global_load_lds_dwordx4 v248, s[70:71]
	s_add_u32 m0, s4, 0x8400
	v_mfma_f32_16x16x32_bf16 v[24:27], v[44:47], v[108:111], v[24:27]
	global_load_lds_dwordx4 v249, s[70:71]
	s_add_u32 m0, s4, 0x8800
	v_mfma_f32_16x16x32_bf16 v[16:19], v[44:47], v[112:115], v[16:19]
	global_load_lds_dwordx4 v250, s[70:71]
	s_add_u32 m0, s4, 0x8c00
	v_mfma_f32_16x16x32_bf16 v[8:11], v[44:47], v[116:119], v[8:11]
	global_load_lds_dwordx4 v251, s[70:71]
	s_add_u32 s68, s68, 0x80
	s_addc_u32 s69, s69, 0
	s_add_u32 s70, s70, 0x80
	s_addc_u32 s71, s71, 0
	s_waitcnt vmcnt(8)
	s_barrier
	ds_read_b128 v[32:35], v252 offset:16384
	ds_read_b128 v[104:107], v254 offset:49152
	ds_read_b128 v[108:111], v254 offset:51200
	ds_read_b128 v[112:115], v254 offset:53248
	ds_read_b128 v[116:119], v254 offset:55296
	ds_read_b128 v[36:39], v252 offset:18432
	ds_read_b128 v[40:43], v252 offset:20480
	ds_read_b128 v[44:47], v252 offset:22528
	v_mfma_f32_16x16x32_bf16 v[92:95], v[48:51], v[120:123], v[92:95]
	v_mfma_f32_16x16x32_bf16 v[88:91], v[48:51], v[124:127], v[88:91]
	v_mfma_f32_16x16x32_bf16 v[84:87], v[48:51], v[136:139], v[84:87]
	v_mfma_f32_16x16x32_bf16 v[80:83], v[48:51], v[144:147], v[80:83]
	v_mfma_f32_16x16x32_bf16 v[76:79], v[52:55], v[120:123], v[76:79]
	v_mfma_f32_16x16x32_bf16 v[72:75], v[52:55], v[124:127], v[72:75]
	v_mfma_f32_16x16x32_bf16 v[68:71], v[52:55], v[136:139], v[68:71]
	v_mfma_f32_16x16x32_bf16 v[60:63], v[52:55], v[144:147], v[60:63]
	v_mfma_f32_16x16x32_bf16 v[28:31], v[56:59], v[120:123], v[28:31]
	v_mfma_f32_16x16x32_bf16 v[20:23], v[56:59], v[124:127], v[20:23]
	v_mfma_f32_16x16x32_bf16 v[4:7], v[56:59], v[136:139], v[4:7]
	v_mfma_f32_16x16x32_bf16 v[12:15], v[56:59], v[144:147], v[12:15]
	v_mfma_f32_16x16x32_bf16 v[0:3], v[64:67], v[120:123], v[0:3]
	v_mfma_f32_16x16x32_bf16 v[24:27], v[64:67], v[124:127], v[24:27]
	v_mfma_f32_16x16x32_bf16 v[16:19], v[64:67], v[136:139], v[16:19]
	v_mfma_f32_16x16x32_bf16 v[8:11], v[64:67], v[144:147], v[8:11]
	ds_read_b128 v[48:51], v253 offset:16384
	ds_read_b128 v[120:123], v255 offset:49152
	ds_read_b128 v[124:127], v255 offset:51200
	ds_read_b128 v[136:139], v255 offset:53248
	ds_read_b128 v[144:147], v255 offset:55296
	ds_read_b128 v[52:55], v253 offset:18432
	ds_read_b128 v[56:59], v253 offset:20480
	ds_read_b128 v[64:67], v253 offset:22528
	s_waitcnt lgkmcnt(14)
	v_mfma_f32_16x16x32_bf16 v[92:95], v[32:35], v[104:107], v[92:95]
	s_waitcnt lgkmcnt(13)
	v_mfma_f32_16x16x32_bf16 v[88:91], v[32:35], v[108:111], v[88:91]
	s_waitcnt lgkmcnt(12)
	v_mfma_f32_16x16x32_bf16 v[84:87], v[32:35], v[112:115], v[84:87]
	s_waitcnt lgkmcnt(11)
	v_mfma_f32_16x16x32_bf16 v[80:83], v[32:35], v[116:119], v[80:83]
	s_waitcnt lgkmcnt(10)
	v_mfma_f32_16x16x32_bf16 v[76:79], v[36:39], v[104:107], v[76:79]
	v_mfma_f32_16x16x32_bf16 v[72:75], v[36:39], v[108:111], v[72:75]
	v_mfma_f32_16x16x32_bf16 v[68:71], v[36:39], v[112:115], v[68:71]
	v_mfma_f32_16x16x32_bf16 v[60:63], v[36:39], v[116:119], v[60:63]
	s_waitcnt lgkmcnt(0)
	s_barrier
	s_add_u32 m0, s4, 0x4000
	v_mfma_f32_16x16x32_bf16 v[28:31], v[40:43], v[104:107], v[28:31]
	global_load_lds_dwordx4 v248, s[68:69]
	s_add_u32 m0, s4, 0x4400
	v_mfma_f32_16x16x32_bf16 v[20:23], v[40:43], v[108:111], v[20:23]
	global_load_lds_dwordx4 v249, s[68:69]
	s_add_u32 m0, s4, 0x4800
	v_mfma_f32_16x16x32_bf16 v[4:7], v[40:43], v[112:115], v[4:7]
	global_load_lds_dwordx4 v250, s[68:69]
	s_add_u32 m0, s4, 0x4c00
	v_mfma_f32_16x16x32_bf16 v[12:15], v[40:43], v[116:119], v[12:15]
	global_load_lds_dwordx4 v251, s[68:69]
	s_add_u32 m0, s4, 0xc000
	v_mfma_f32_16x16x32_bf16 v[0:3], v[44:47], v[104:107], v[0:3]
	global_load_lds_dwordx4 v248, s[70:71]
	s_add_u32 m0, s4, 0xc400
	v_mfma_f32_16x16x32_bf16 v[24:27], v[44:47], v[108:111], v[24:27]
	global_load_lds_dwordx4 v249, s[70:71]
	s_add_u32 m0, s4, 0xc800
	v_mfma_f32_16x16x32_bf16 v[16:19], v[44:47], v[112:115], v[16:19]
	global_load_lds_dwordx4 v250, s[70:71]
	s_add_u32 m0, s4, 0xcc00
	v_mfma_f32_16x16x32_bf16 v[8:11], v[44:47], v[116:119], v[8:11]
	global_load_lds_dwordx4 v251, s[70:71]
	s_add_u32 s68, s68, 0x80
	s_addc_u32 s69, s69, 0
	s_add_u32 s70, s70, 0x80
	s_addc_u32 s71, s71, 0
	s_mov_b32 s32, 14
.Lg28_loop:
	s_waitcnt vmcnt(8)
	s_barrier
	ds_read_b128 v[32:35], v252 offset:0
	ds_read_b128 v[104:107], v254 offset:32768
	ds_read_b128 v[108:111], v254 offset:34816
	ds_read_b128 v[112:115], v254 offset:36864
	ds_read_b128 v[116:119], v254 offset:38912
	ds_read_b128 v[36:39], v252 offset:2048
	ds_read_b128 v[40:43], v252 offset:4096
	ds_read_b128 v[44:47], v252 offset:6144
	v_mfma_f32_16x16x32_bf16 v[92:95], v[48:51], v[120:123], v[92:95]
	v_mfma_f32_16x16x32_bf16 v[88:91], v[48:51], v[124:127], v[88:91]
	v_mfma_f32_16x16x32_bf16 v[84:87], v[48:51], v[136:139], v[84:87]
	v_mfma_f32_16x16x32_bf16 v[80:83], v[48:51], v[144:147], v[80:83]
	v_mfma_f32_16x16x32_bf16 v[76:79], v[52:55], v[120:123], v[76:79]
	v_mfma_f32_16x16x32_bf16 v[72:75], v[52:55], v[124:127], v[72:75]
	v_mfma_f32_16x16x32_bf16 v[68:71], v[52:55], v[136:139], v[68:71]
	v_mfma_f32_16x16x32_bf16 v[60:63], v[52:55], v[144:147], v[60:63]
	v_mfma_f32_16x16x32_bf16 v[28:31], v[56:59], v[120:123], v[28:31]
	v_mfma_f32_16x16x32_bf16 v[20:23], v[56:59], v[124:127], v[20:23]
	v_mfma_f32_16x16x32_bf16 v[4:7], v[56:59], v[136:139], v[4:7]
	v_mfma_f32_16x16x32_bf16 v[12:15], v[56:59], v[144:147], v[12:15]
	v_mfma_f32_16x16x32_bf16 v[0:3], v[64:67], v[120:123], v[0:3]
	v_mfma_f32_16x16x32_bf16 v[24:27], v[64:67], v[124:127], v[24:27]
	v_mfma_f32_16x16x32_bf16 v[16:19], v[64:67], v[136:139], v[16:19]
	v_mfma_f32_16x16x32_bf16 v[8:11], v[64:67], v[144:147], v[8:11]
	ds_read_b128 v[48:51], v253 offset:0
	ds_read_b128 v[120:123], v255 offset:32768
	ds_read_b128 v[124:127], v255 offset:34816
	ds_read_b128 v[136:139], v255 offset:36864
	ds_read_b128 v[144:147], v255 offset:38912
	ds_read_b128 v[52:55], v253 offset:2048
	ds_read_b128 v[56:59], v253 offset:4096
	ds_read_b128 v[64:67], v253 offset:6144
	s_waitcnt lgkmcnt(14)
	v_mfma_f32_16x16x32_bf16 v[92:95], v[32:35], v[104:107], v[92:95]
	s_waitcnt lgkmcnt(13)
	v_mfma_f32_16x16x32_bf16 v[88:91], v[32:35], v[108:111], v[88:91]
	s_waitcnt lgkmcnt(12)
	v_mfma_f32_16x16x32_bf16 v[84:87], v[32:35], v[112:115], v[84:87]
	s_waitcnt lgkmcnt(11)
	v_mfma_f32_16x16x32_bf16 v[80:83], v[32:35], v[116:119], v[80:83]
	s_waitcnt lgkmcnt(10)
	v_mfma_f32_16x16x32_bf16 v[76:79], v[36:39], v[104:107], v[76:79]
	v_mfma_f32_16x16x32_bf16 v[72:75], v[36:39], v[108:111], v[72:75]
	v_mfma_f32_16x16x32_bf16 v[68:71], v[36:39], v[112:115], v[68:71]
	v_mfma_f32_16x16x32_bf16 v[60:63], v[36:39], v[116:119], v[60:63]
	s_waitcnt lgkmcnt(0)
	s_barrier
	s_add_u32 m0, s4, 0x0
	v_mfma_f32_16x16x32_bf16 v[28:31], v[40:43], v[104:107], v[28:31]
	global_load_lds_dwordx4 v248, s[68:69]
	s_add_u32 m0, s4, 0x400
	v_mfma_f32_16x16x32_bf16 v[20:23], v[40:43], v[108:111], v[20:23]
	global_load_lds_dwordx4 v249, s[68:69]
	s_add_u32 m0, s4, 0x800
	v_mfma_f32_16x16x32_bf16 v[4:7], v[40:43], v[112:115], v[4:7]
	global_load_lds_dwordx4 v250, s[68:69]
	s_add_u32 m0, s4, 0xc00
	v_mfma_f32_16x16x32_bf16 v[12:15], v[40:43], v[116:119], v[12:15]
	global_load_lds_dwordx4 v251, s[68:69]
	s_add_u32 m0, s4, 0x8000
	v_mfma_f32_16x16x32_bf16 v[0:3], v[44:47], v[104:107], v[0:3]
	global_load_lds_dwordx4 v248, s[70:71]
	s_add_u32 m0, s4, 0x8400
	v_mfma_f32_16x16x32_bf16 v[24:27], v[44:47], v[108:111], v[24:27]
	global_load_lds_dwordx4 v249, s[70:71]
	s_add_u32 m0, s4, 0x8800
	v_mfma_f32_16x16x32_bf16 v[16:19], v[44:47], v[112:115], v[16:19]
	global_load_lds_dwordx4 v250, s[70:71]
	s_add_u32 m0, s4, 0x8c00
	v_mfma_f32_16x16x32_bf16 v[8:11], v[44:47], v[116:119], v[8:11]
	global_load_lds_dwordx4 v251, s[70:71]
	s_add_u32 s68, s68, 0x80
	s_addc_u32 s69, s69, 0
	s_add_u32 s70, s70, 0x80
	s_addc_u32 s71, s71, 0
	s_waitcnt vmcnt(8)
	s_barrier
	ds_read_b128 v[32:35], v252 offset:16384
	ds_read_b128 v[104:107], v254 offset:49152
	ds_read_b128 v[108:111], v254 offset:51200
	ds_read_b128 v[112:115], v254 offset:53248
	ds_read_b128 v[116:119], v254 offset:55296
	ds_read_b128 v[36:39], v252 offset:18432
	ds_read_b128 v[40:43], v252 offset:20480
	ds_read_b128 v[44:47], v252 offset:22528
	v_mfma_f32_16x16x32_bf16 v[92:95], v[48:51], v[120:123], v[92:95]
	v_mfma_f32_16x16x32_bf16 v[88:91], v[48:51], v[124:127], v[88:91]
	v_mfma_f32_16x16x32_bf16 v[84:87], v[48:51], v[136:139], v[84:87]
	v_mfma_f32_16x16x32_bf16 v[80:83], v[48:51], v[144:147], v[80:83]
	v_mfma_f32_16x16x32_bf16 v[76:79], v[52:55], v[120:123], v[76:79]
	v_mfma_f32_16x16x32_bf16 v[72:75], v[52:55], v[124:127], v[72:75]
	v_mfma_f32_16x16x32_bf16 v[68:71], v[52:55], v[136:139], v[68:71]
	v_mfma_f32_16x16x32_bf16 v[60:63], v[52:55], v[144:147], v[60:63]
	v_mfma_f32_16x16x32_bf16 v[28:31], v[56:59], v[120:123], v[28:31]
	v_mfma_f32_16x16x32_bf16 v[20:23], v[56:59], v[124:127], v[20:23]
	v_mfma_f32_16x16x32_bf16 v[4:7], v[56:59], v[136:139], v[4:7]
	v_mfma_f32_16x16x32_bf16 v[12:15], v[56:59], v[144:147], v[12:15]
	v_mfma_f32_16x16x32_bf16 v[0:3], v[64:67], v[120:123], v[0:3]
	v_mfma_f32_16x16x32_bf16 v[24:27], v[64:67], v[124:127], v[24:27]
	v_mfma_f32_16x16x32_bf16 v[16:19], v[64:67], v[136:139], v[16:19]
	v_mfma_f32_16x16x32_bf16 v[8:11], v[64:67], v[144:147], v[8:11]
	ds_read_b128 v[48:51], v253 offset:16384
	ds_read_b128 v[120:123], v255 offset:49152
	ds_read_b128 v[124:127], v255 offset:51200
	ds_read_b128 v[136:139], v255 offset:53248
	ds_read_b128 v[144:147], v255 offset:55296
	ds_read_b128 v[52:55], v253 offset:18432
	ds_read_b128 v[56:59], v253 offset:20480
	ds_read_b128 v[64:67], v253 offset:22528
	s_waitcnt lgkmcnt(14)
	v_mfma_f32_16x16x32_bf16 v[92:95], v[32:35], v[104:107], v[92:95]
	s_waitcnt lgkmcnt(13)
	v_mfma_f32_16x16x32_bf16 v[88:91], v[32:35], v[108:111], v[88:91]
	s_waitcnt lgkmcnt(12)
	v_mfma_f32_16x16x32_bf16 v[84:87], v[32:35], v[112:115], v[84:87]
	s_waitcnt lgkmcnt(11)
	v_mfma_f32_16x16x32_bf16 v[80:83], v[32:35], v[116:119], v[80:83]
	s_waitcnt lgkmcnt(10)
	v_mfma_f32_16x16x32_bf16 v[76:79], v[36:39], v[104:107], v[76:79]
	v_mfma_f32_16x16x32_bf16 v[72:75], v[36:39], v[108:111], v[72:75]
	v_mfma_f32_16x16x32_bf16 v[68:71], v[36:39], v[112:115], v[68:71]
	v_mfma_f32_16x16x32_bf16 v[60:63], v[36:39], v[116:119], v[60:63]
	s_waitcnt lgkmcnt(0)
	s_barrier
	s_add_u32 m0, s4, 0x4000
	v_mfma_f32_16x16x32_bf16 v[28:31], v[40:43], v[104:107], v[28:31]
	global_load_lds_dwordx4 v248, s[68:69]
	s_add_u32 m0, s4, 0x4400
	v_mfma_f32_16x16x32_bf16 v[20:23], v[40:43], v[108:111], v[20:23]
	global_load_lds_dwordx4 v249, s[68:69]
	s_add_u32 m0, s4, 0x4800
	v_mfma_f32_16x16x32_bf16 v[4:7], v[40:43], v[112:115], v[4:7]
	global_load_lds_dwordx4 v250, s[68:69]
	s_add_u32 m0, s4, 0x4c00
	v_mfma_f32_16x16x32_bf16 v[12:15], v[40:43], v[116:119], v[12:15]
	global_load_lds_dwordx4 v251, s[68:69]
	s_add_u32 m0, s4, 0xc000
	v_mfma_f32_16x16x32_bf16 v[0:3], v[44:47], v[104:107], v[0:3]
	global_load_lds_dwordx4 v248, s[70:71]
	s_add_u32 m0, s4, 0xc400
	v_mfma_f32_16x16x32_bf16 v[24:27], v[44:47], v[108:111], v[24:27]
	global_load_lds_dwordx4 v249, s[70:71]
	s_add_u32 m0, s4, 0xc800
	v_mfma_f32_16x16x32_bf16 v[16:19], v[44:47], v[112:115], v[16:19]
	global_load_lds_dwordx4 v250, s[70:71]
	s_add_u32 m0, s4, 0xcc00
	v_mfma_f32_16x16x32_bf16 v[8:11], v[44:47], v[116:119], v[8:11]
	global_load_lds_dwordx4 v251, s[70:71]
	s_add_u32 s68, s68, 0x80
	s_addc_u32 s69, s69, 0
	s_add_u32 s70, s70, 0x80
	s_addc_u32 s71, s71, 0
	s_sub_u32 s32, s32, 1
	s_cmp_lg_u32 s32, 0
	s_cbranch_scc1 .Lg28_loop
	s_waitcnt vmcnt(8)
	s_barrier
	ds_read_b128 v[32:35], v252 offset:0
	ds_read_b128 v[104:107], v254 offset:32768
	ds_read_b128 v[108:111], v254 offset:34816
	ds_read_b128 v[112:115], v254 offset:36864
	ds_read_b128 v[116:119], v254 offset:38912
	ds_read_b128 v[36:39], v252 offset:2048
	ds_read_b128 v[40:43], v252 offset:4096
	ds_read_b128 v[44:47], v252 offset:6144
	v_mfma_f32_16x16x32_bf16 v[92:95], v[48:51], v[120:123], v[92:95]
	v_mfma_f32_16x16x32_bf16 v[88:91], v[48:51], v[124:127], v[88:91]
	v_mfma_f32_16x16x32_bf16 v[84:87], v[48:51], v[136:139], v[84:87]
	v_mfma_f32_16x16x32_bf16 v[80:83], v[48:51], v[144:147], v[80:83]
	v_mfma_f32_16x16x32_bf16 v[76:79], v[52:55], v[120:123], v[76:79]
	v_mfma_f32_16x16x32_bf16 v[72:75], v[52:55], v[124:127], v[72:75]
	v_mfma_f32_16x16x32_bf16 v[68:71], v[52:55], v[136:139], v[68:71]
	v_mfma_f32_16x16x32_bf16 v[60:63], v[52:55], v[144:147], v[60:63]
	v_mfma_f32_16x16x32_bf16 v[28:31], v[56:59], v[120:123], v[28:31]
	v_mfma_f32_16x16x32_bf16 v[20:23], v[56:59], v[124:127], v[20:23]
	v_mfma_f32_16x16x32_bf16 v[4:7], v[56:59], v[136:139], v[4:7]
	v_mfma_f32_16x16x32_bf16 v[12:15], v[56:59], v[144:147], v[12:15]
	v_mfma_f32_16x16x32_bf16 v[0:3], v[64:67], v[120:123], v[0:3]
	v_mfma_f32_16x16x32_bf16 v[24:27], v[64:67], v[124:127], v[24:27]
	v_mfma_f32_16x16x32_bf16 v[16:19], v[64:67], v[136:139], v[16:19]
	v_mfma_f32_16x16x32_bf16 v[8:11], v[64:67], v[144:147], v[8:11]
	ds_read_b128 v[48:51], v253 offset:0
	ds_read_b128 v[120:123], v255 offset:32768
	ds_read_b128 v[124:127], v255 offset:34816
	ds_read_b128 v[136:139], v255 offset:36864
	ds_read_b128 v[144:147], v255 offset:38912
	ds_read_b128 v[52:55], v253 offset:2048
	ds_read_b128 v[56:59], v253 offset:4096
	ds_read_b128 v[64:67], v253 offset:6144
	s_waitcnt lgkmcnt(14)
	v_mfma_f32_16x16x32_bf16 v[92:95], v[32:35], v[104:107], v[92:95]
	s_waitcnt lgkmcnt(13)
	v_mfma_f32_16x16x32_bf16 v[88:91], v[32:35], v[108:111], v[88:91]
	s_waitcnt lgkmcnt(12)
	v_mfma_f32_16x16x32_bf16 v[84:87], v[32:35], v[112:115], v[84:87]
	s_waitcnt lgkmcnt(11)
	v_mfma_f32_16x16x32_bf16 v[80:83], v[32:35], v[116:119], v[80:83]
	s_waitcnt lgkmcnt(10)
	v_mfma_f32_16x16x32_bf16 v[76:79], v[36:39], v[104:107], v[76:79]
	v_mfma_f32_16x16x32_bf16 v[72:75], v[36:39], v[108:111], v[72:75]
	v_mfma_f32_16x16x32_bf16 v[68:71], v[36:39], v[112:115], v[68:71]
	v_mfma_f32_16x16x32_bf16 v[60:63], v[36:39], v[116:119], v[60:63]
	s_waitcnt lgkmcnt(0)
	s_barrier
	v_mfma_f32_16x16x32_bf16 v[28:31], v[40:43], v[104:107], v[28:31]
	v_mfma_f32_16x16x32_bf16 v[20:23], v[40:43], v[108:111], v[20:23]
	v_mfma_f32_16x16x32_bf16 v[4:7], v[40:43], v[112:115], v[4:7]
	v_mfma_f32_16x16x32_bf16 v[12:15], v[40:43], v[116:119], v[12:15]
	v_mfma_f32_16x16x32_bf16 v[0:3], v[44:47], v[104:107], v[0:3]
	v_mfma_f32_16x16x32_bf16 v[24:27], v[44:47], v[108:111], v[24:27]
	v_mfma_f32_16x16x32_bf16 v[16:19], v[44:47], v[112:115], v[16:19]
	v_mfma_f32_16x16x32_bf16 v[8:11], v[44:47], v[116:119], v[8:11]
	s_waitcnt vmcnt(0)
	s_barrier
	ds_read_b128 v[32:35], v252 offset:16384
	ds_read_b128 v[104:107], v254 offset:49152
	ds_read_b128 v[108:111], v254 offset:51200
	ds_read_b128 v[112:115], v254 offset:53248
	ds_read_b128 v[116:119], v254 offset:55296
	ds_read_b128 v[36:39], v252 offset:18432
	ds_read_b128 v[40:43], v252 offset:20480
	ds_read_b128 v[44:47], v252 offset:22528
	v_mfma_f32_16x16x32_bf16 v[92:95], v[48:51], v[120:123], v[92:95]
	v_mfma_f32_16x16x32_bf16 v[88:91], v[48:51], v[124:127], v[88:91]
	v_mfma_f32_16x16x32_bf16 v[84:87], v[48:51], v[136:139], v[84:87]
	v_mfma_f32_16x16x32_bf16 v[80:83], v[48:51], v[144:147], v[80:83]
	v_mfma_f32_16x16x32_bf16 v[76:79], v[52:55], v[120:123], v[76:79]
	v_mfma_f32_16x16x32_bf16 v[72:75], v[52:55], v[124:127], v[72:75]
	v_mfma_f32_16x16x32_bf16 v[68:71], v[52:55], v[136:139], v[68:71]
	v_mfma_f32_16x16x32_bf16 v[60:63], v[52:55], v[144:147], v[60:63]
	v_mfma_f32_16x16x32_bf16 v[28:31], v[56:59], v[120:123], v[28:31]
	v_mfma_f32_16x16x32_bf16 v[20:23], v[56:59], v[124:127], v[20:23]
	v_mfma_f32_16x16x32_bf16 v[4:7], v[56:59], v[136:139], v[4:7]
	v_mfma_f32_16x16x32_bf16 v[12:15], v[56:59], v[144:147], v[12:15]
	v_mfma_f32_16x16x32_bf16 v[0:3], v[64:67], v[120:123], v[0:3]
	v_mfma_f32_16x16x32_bf16 v[24:27], v[64:67], v[124:127], v[24:27]
	v_mfma_f32_16x16x32_bf16 v[16:19], v[64:67], v[136:139], v[16:19]
	v_mfma_f32_16x16x32_bf16 v[8:11], v[64:67], v[144:147], v[8:11]
	ds_read_b128 v[48:51], v253 offset:16384
	ds_read_b128 v[120:123], v255 offset:49152
	ds_read_b128 v[124:127], v255 offset:51200
	ds_read_b128 v[136:139], v255 offset:53248
	ds_read_b128 v[144:147], v255 offset:55296
	ds_read_b128 v[52:55], v253 offset:18432
	ds_read_b128 v[56:59], v253 offset:20480
	ds_read_b128 v[64:67], v253 offset:22528
	s_waitcnt lgkmcnt(14)
	v_mfma_f32_16x16x32_bf16 v[92:95], v[32:35], v[104:107], v[92:95]
	s_waitcnt lgkmcnt(13)
	v_mfma_f32_16x16x32_bf16 v[88:91], v[32:35], v[108:111], v[88:91]
	s_waitcnt lgkmcnt(12)
	v_mfma_f32_16x16x32_bf16 v[84:87], v[32:35], v[112:115], v[84:87]
	s_waitcnt lgkmcnt(11)
	v_mfma_f32_16x16x32_bf16 v[80:83], v[32:35], v[116:119], v[80:83]
	s_waitcnt lgkmcnt(10)
	v_mfma_f32_16x16x32_bf16 v[76:79], v[36:39], v[104:107], v[76:79]
	v_mfma_f32_16x16x32_bf16 v[72:75], v[36:39], v[108:111], v[72:75]
	v_mfma_f32_16x16x32_bf16 v[68:71], v[36:39], v[112:115], v[68:71]
	v_mfma_f32_16x16x32_bf16 v[60:63], v[36:39], v[116:119], v[60:63]
	s_waitcnt lgkmcnt(0)
	s_barrier
	v_mfma_f32_16x16x32_bf16 v[28:31], v[40:43], v[104:107], v[28:31]
	v_mfma_f32_16x16x32_bf16 v[20:23], v[40:43], v[108:111], v[20:23]
	v_mfma_f32_16x16x32_bf16 v[4:7], v[40:43], v[112:115], v[4:7]
	v_mfma_f32_16x16x32_bf16 v[12:15], v[40:43], v[116:119], v[12:15]
	v_mfma_f32_16x16x32_bf16 v[0:3], v[44:47], v[104:107], v[0:3]
	v_mfma_f32_16x16x32_bf16 v[24:27], v[44:47], v[108:111], v[24:27]
	v_mfma_f32_16x16x32_bf16 v[16:19], v[44:47], v[112:115], v[16:19]
	v_mfma_f32_16x16x32_bf16 v[8:11], v[44:47], v[116:119], v[8:11]
	v_mfma_f32_16x16x32_bf16 v[92:95], v[48:51], v[120:123], v[92:95]
	v_mfma_f32_16x16x32_bf16 v[88:91], v[48:51], v[124:127], v[88:91]
	v_mfma_f32_16x16x32_bf16 v[84:87], v[48:51], v[136:139], v[84:87]
	v_mfma_f32_16x16x32_bf16 v[80:83], v[48:51], v[144:147], v[80:83]
	v_mfma_f32_16x16x32_bf16 v[76:79], v[52:55], v[120:123], v[76:79]
	v_mfma_f32_16x16x32_bf16 v[72:75], v[52:55], v[124:127], v[72:75]
	v_mfma_f32_16x16x32_bf16 v[68:71], v[52:55], v[136:139], v[68:71]
	v_mfma_f32_16x16x32_bf16 v[60:63], v[52:55], v[144:147], v[60:63]
	v_mfma_f32_16x16x32_bf16 v[28:31], v[56:59], v[120:123], v[28:31]
	v_mfma_f32_16x16x32_bf16 v[20:23], v[56:59], v[124:127], v[20:23]
	v_mfma_f32_16x16x32_bf16 v[4:7], v[56:59], v[136:139], v[4:7]
	v_mfma_f32_16x16x32_bf16 v[12:15], v[56:59], v[144:147], v[12:15]
	v_mfma_f32_16x16x32_bf16 v[0:3], v[64:67], v[120:123], v[0:3]
	v_mfma_f32_16x16x32_bf16 v[24:27], v[64:67], v[124:127], v[24:27]
	v_mfma_f32_16x16x32_bf16 v[16:19], v[64:67], v[136:139], v[16:19]
	v_mfma_f32_16x16x32_bf16 v[8:11], v[64:67], v[144:147], v[8:11]
	s_nop 7
	s_nop 1
	s_branch .Lg28_join
.Lg28_light:
	v_readfirstlane_b32 s68, v102
	v_readfirstlane_b32 s69, v103
	v_readfirstlane_b32 s70, v104
	v_readfirstlane_b32 s71, v105
	v_readfirstlane_b32 s4, v247
	s_nop 3
	s_mul_i32 s67, s4, 0x2000
	s_sub_u32 s68, s68, s67
	s_subb_u32 s69, s69, 0
	s_sub_u32 s70, s70, s67
	s_subb_u32 s71, s71, 0
	s_lshl_b32 s4, s4, 12
	s_add_u32 m0, s4, 0x0
	v_mov_b32_e32 v92, 0
	global_load_lds_dwordx4 v236, s[68:69]
	v_mov_b32_e32 v93, 0
	s_add_u32 m0, s4, 0x400
	v_mov_b32_e32 v94, 0
	global_load_lds_dwordx4 v237, s[68:69]
	v_mov_b32_e32 v95, 0
	s_add_u32 m0, s4, 0x800
	v_mov_b32_e32 v88, 0
	global_load_lds_dwordx4 v238, s[68:69]
	v_mov_b32_e32 v89, 0
	s_add_u32 m0, s4, 0xc00
	v_mov_b32_e32 v90, 0
	global_load_lds_dwordx4 v239, s[68:69]
	v_mov_b32_e32 v91, 0
	s_add_u32 m0, s4, 0x8000
	v_mov_b32_e32 v84, 0
	global_load_lds_dwordx4 v236, s[70:71]
	v_mov_b32_e32 v85, 0
	s_add_u32 m0, s4, 0x8400
	v_mov_b32_e32 v86, 0
	global_load_lds_dwordx4 v237, s[70:71]
	v_mov_b32_e32 v87, 0
	s_add_u32 m0, s4, 0x8800
	v_mov_b32_e32 v80, 0
	global_load_lds_dwordx4 v238, s[70:71]
	v_mov_b32_e32 v81, 0
	s_add_u32 m0, s4, 0x8c00
	v_mov_b32_e32 v82, 0
	global_load_lds_dwordx4 v239, s[70:71]
	v_mov_b32_e32 v83, 0
	s_add_u32 s68, s68, 0x80
	s_addc_u32 s69, s69, 0
	s_add_u32 s70, s70, 0x80
	s_addc_u32 s71, s71, 0
	s_add_u32 m0, s4, 0x4000
	v_mov_b32_e32 v76, 0
	global_load_lds_dwordx4 v236, s[68:69]
	v_mov_b32_e32 v77, 0
	s_add_u32 m0, s4, 0x4400
	v_mov_b32_e32 v78, 0
	global_load_lds_dwordx4 v237, s[68:69]
	v_mov_b32_e32 v79, 0
	s_add_u32 m0, s4, 0x4800
	v_mov_b32_e32 v72, 0
	global_load_lds_dwordx4 v238, s[68:69]
	v_mov_b32_e32 v73, 0
	s_add_u32 m0, s4, 0x4c00
	v_mov_b32_e32 v74, 0
	global_load_lds_dwordx4 v239, s[68:69]
	v_mov_b32_e32 v75, 0
	s_add_u32 m0, s4, 0xc000
	v_mov_b32_e32 v68, 0
	global_load_lds_dwordx4 v236, s[70:71]
	v_mov_b32_e32 v69, 0
	s_add_u32 m0, s4, 0xc400
	v_mov_b32_e32 v70, 0
	global_load_lds_dwordx4 v237, s[70:71]
	v_mov_b32_e32 v71, 0
	s_add_u32 m0, s4, 0xc800
	v_mov_b32_e32 v60, 0
	global_load_lds_dwordx4 v238, s[70:71]
	v_mov_b32_e32 v61, 0
	s_add_u32 m0, s4, 0xcc00
	v_mov_b32_e32 v62, 0
	global_load_lds_dwordx4 v239, s[70:71]
	v_mov_b32_e32 v63, 0
	s_add_u32 s68, s68, 0x80
	s_addc_u32 s69, s69, 0
	s_add_u32 s70, s70, 0x80
	s_addc_u32 s71, s71, 0
	v_mov_b32_e32 v28, 0
	v_mov_b32_e32 v29, 0
	v_mov_b32_e32 v30, 0
	v_mov_b32_e32 v31, 0
	v_mov_b32_e32 v20, 0
	v_mov_b32_e32 v21, 0
	v_mov_b32_e32 v22, 0
	v_mov_b32_e32 v23, 0
	v_mov_b32_e32 v4, 0
	v_mov_b32_e32 v5, 0
	v_mov_b32_e32 v6, 0
	v_mov_b32_e32 v7, 0
	v_mov_b32_e32 v12, 0
	v_mov_b32_e32 v13, 0
	v_mov_b32_e32 v14, 0
	v_mov_b32_e32 v15, 0
	v_mov_b32_e32 v0, 0
	v_mov_b32_e32 v1, 0
	v_mov_b32_e32 v2, 0
	v_mov_b32_e32 v3, 0
	v_mov_b32_e32 v24, 0
	v_mov_b32_e32 v25, 0
	v_mov_b32_e32 v26, 0
	v_mov_b32_e32 v27, 0
	v_mov_b32_e32 v16, 0
	v_mov_b32_e32 v17, 0
	v_mov_b32_e32 v18, 0
	v_mov_b32_e32 v19, 0
	v_mov_b32_e32 v8, 0
	v_mov_b32_e32 v9, 0
	v_mov_b32_e32 v10, 0
	v_mov_b32_e32 v11, 0
	s_waitcnt vmcnt(8)
	s_barrier
	ds_read_b128 v[32:35], v252 offset:0
	ds_read_b128 v[104:107], v254 offset:32768
	ds_read_b128 v[108:111], v254 offset:34816
	ds_read_b128 v[112:115], v254 offset:36864
	ds_read_b128 v[116:119], v254 offset:38912
	ds_read_b128 v[36:39], v252 offset:2048
	ds_read_b128 v[40:43], v252 offset:4096
	ds_read_b128 v[44:47], v252 offset:6144
	ds_read_b128 v[48:51], v253 offset:0
	ds_read_b128 v[120:123], v255 offset:32768
	ds_read_b128 v[124:127], v255 offset:34816
	ds_read_b128 v[136:139], v255 offset:36864
	ds_read_b128 v[144:147], v255 offset:38912
	s_waitcnt lgkmcnt(11)
	v_mfma_f32_16x16x32_bf16 v[92:95], v[32:35], v[104:107], v[92:95]
	s_waitcnt lgkmcnt(10)
	v_mfma_f32_16x16x32_bf16 v[88:91], v[32:35], v[108:111], v[88:91]
	s_waitcnt lgkmcnt(9)
	v_mfma_f32_16x16x32_bf16 v[84:87], v[32:35], v[112:115], v[84:87]
	s_waitcnt lgkmcnt(8)
	v_mfma_f32_16x16x32_bf16 v[80:83], v[32:35], v[116:119], v[80:83]
	ds_read_b128 v[52:55], v253 offset:2048
	ds_read_b128 v[56:59], v253 offset:4096
	ds_read_b128 v[64:67], v253 offset:6144
	s_waitcnt lgkmcnt(10)
	v_mfma_f32_16x16x32_bf16 v[76:79], v[36:39], v[104:107], v[76:79]
	v_mfma_f32_16x16x32_bf16 v[72:75], v[36:39], v[108:111], v[72:75]
	v_mfma_f32_16x16x32_bf16 v[68:71], v[36:39], v[112:115], v[68:71]
	v_mfma_f32_16x16x32_bf16 v[60:63], v[36:39], v[116:119], v[60:63]
	s_waitcnt lgkmcnt(0)
	s_barrier
	s_add_u32 m0, s4, 0x0
	v_mfma_f32_16x16x32_bf16 v[28:31], v[40:43], v[104:107], v[28:31]
	global_load_lds_dwordx4 v236, s[68:69]
	s_add_u32 m0, s4, 0x400
	v_mfma_f32_16x16x32_bf16 v[20:23], v[40:43], v[108:111], v[20:23]
	global_load_lds_dwordx4 v237, s[68:69]
	s_add_u32 m0, s4, 0x800
	v_mfma_f32_16x16x32_bf16 v[4:7], v[40:43], v[112:115], v[4:7]
	global_load_lds_dwordx4 v238, s[68:69]
	s_add_u32 m0, s4, 0xc00
	v_mfma_f32_16x16x32_bf16 v[12:15], v[40:43], v[116:119], v[12:15]
	global_load_lds_dwordx4 v239, s[68:69]
	s_add_u32 m0, s4, 0x8000
	v_mfma_f32_16x16x32_bf16 v[0:3], v[44:47], v[104:107], v[0:3]
	global_load_lds_dwordx4 v236, s[70:71]
	s_add_u32 m0, s4, 0x8400
	v_mfma_f32_16x16x32_bf16 v[24:27], v[44:47], v[108:111], v[24:27]
	global_load_lds_dwordx4 v237, s[70:71]
	s_add_u32 m0, s4, 0x8800
	v_mfma_f32_16x16x32_bf16 v[16:19], v[44:47], v[112:115], v[16:19]
	global_load_lds_dwordx4 v238, s[70:71]
	s_add_u32 m0, s4, 0x8c00
	v_mfma_f32_16x16x32_bf16 v[8:11], v[44:47], v[116:119], v[8:11]
	global_load_lds_dwordx4 v239, s[70:71]
	s_add_u32 s68, s68, 0x80
	s_addc_u32 s69, s69, 0
	s_add_u32 s70, s70, 0x80
	s_addc_u32 s71, s71, 0
	s_waitcnt vmcnt(8)
	s_barrier
	ds_read_b128 v[32:35], v252 offset:16384
	ds_read_b128 v[104:107], v254 offset:49152
	ds_read_b128 v[108:111], v254 offset:51200
	ds_read_b128 v[112:115], v254 offset:53248
	ds_read_b128 v[116:119], v254 offset:55296
	ds_read_b128 v[36:39], v252 offset:18432
	ds_read_b128 v[40:43], v252 offset:20480
	ds_read_b128 v[44:47], v252 offset:22528
	v_mfma_f32_16x16x32_bf16 v[92:95], v[48:51], v[120:123], v[92:95]
	v_mfma_f32_16x16x32_bf16 v[88:91], v[48:51], v[124:127], v[88:91]
	v_mfma_f32_16x16x32_bf16 v[84:87], v[48:51], v[136:139], v[84:87]
	v_mfma_f32_16x16x32_bf16 v[80:83], v[48:51], v[144:147], v[80:83]
	v_mfma_f32_16x16x32_bf16 v[76:79], v[52:55], v[120:123], v[76:79]
	v_mfma_f32_16x16x32_bf16 v[72:75], v[52:55], v[124:127], v[72:75]
	v_mfma_f32_16x16x32_bf16 v[68:71], v[52:55], v[136:139], v[68:71]
	v_mfma_f32_16x16x32_bf16 v[60:63], v[52:55], v[144:147], v[60:63]
	v_mfma_f32_16x16x32_bf16 v[28:31], v[56:59], v[120:123], v[28:31]
	v_mfma_f32_16x16x32_bf16 v[20:23], v[56:59], v[124:127], v[20:23]
	v_mfma_f32_16x16x32_bf16 v[4:7], v[56:59], v[136:139], v[4:7]
	v_mfma_f32_16x16x32_bf16 v[12:15], v[56:59], v[144:147], v[12:15]
	v_mfma_f32_16x16x32_bf16 v[0:3], v[64:67], v[120:123], v[0:3]
	v_mfma_f32_16x16x32_bf16 v[24:27], v[64:67], v[124:127], v[24:27]
	v_mfma_f32_16x16x32_bf16 v[16:19], v[64:67], v[136:139], v[16:19]
	v_mfma_f32_16x16x32_bf16 v[8:11], v[64:67], v[144:147], v[8:11]
	ds_read_b128 v[48:51], v253 offset:16384
	ds_read_b128 v[120:123], v255 offset:49152
	ds_read_b128 v[124:127], v255 offset:51200
	ds_read_b128 v[136:139], v255 offset:53248
	ds_read_b128 v[144:147], v255 offset:55296
	ds_read_b128 v[52:55], v253 offset:18432
	ds_read_b128 v[56:59], v253 offset:20480
	ds_read_b128 v[64:67], v253 offset:22528
	s_waitcnt lgkmcnt(14)
	v_mfma_f32_16x16x32_bf16 v[92:95], v[32:35], v[104:107], v[92:95]
	s_waitcnt lgkmcnt(13)
	v_mfma_f32_16x16x32_bf16 v[88:91], v[32:35], v[108:111], v[88:91]
	s_waitcnt lgkmcnt(12)
	v_mfma_f32_16x16x32_bf16 v[84:87], v[32:35], v[112:115], v[84:87]
	s_waitcnt lgkmcnt(11)
	v_mfma_f32_16x16x32_bf16 v[80:83], v[32:35], v[116:119], v[80:83]
	s_waitcnt lgkmcnt(10)
	v_mfma_f32_16x16x32_bf16 v[76:79], v[36:39], v[104:107], v[76:79]
	v_mfma_f32_16x16x32_bf16 v[72:75], v[36:39], v[108:111], v[72:75]
	v_mfma_f32_16x16x32_bf16 v[68:71], v[36:39], v[112:115], v[68:71]
	v_mfma_f32_16x16x32_bf16 v[60:63], v[36:39], v[116:119], v[60:63]
	s_waitcnt lgkmcnt(0)
	s_barrier
	s_add_u32 m0, s4, 0x4000
	v_mfma_f32_16x16x32_bf16 v[28:31], v[40:43], v[104:107], v[28:31]
	global_load_lds_dwordx4 v236, s[68:69]
	s_add_u32 m0, s4, 0x4400
	v_mfma_f32_16x16x32_bf16 v[20:23], v[40:43], v[108:111], v[20:23]
	global_load_lds_dwordx4 v237, s[68:69]
	s_add_u32 m0, s4, 0x4800
	v_mfma_f32_16x16x32_bf16 v[4:7], v[40:43], v[112:115], v[4:7]
	global_load_lds_dwordx4 v238, s[68:69]
	s_add_u32 m0, s4, 0x4c00
	v_mfma_f32_16x16x32_bf16 v[12:15], v[40:43], v[116:119], v[12:15]
	global_load_lds_dwordx4 v239, s[68:69]
	s_add_u32 m0, s4, 0xc000
	v_mfma_f32_16x16x32_bf16 v[0:3], v[44:47], v[104:107], v[0:3]
	global_load_lds_dwordx4 v236, s[70:71]
	s_add_u32 m0, s4, 0xc400
	v_mfma_f32_16x16x32_bf16 v[24:27], v[44:47], v[108:111], v[24:27]
	global_load_lds_dwordx4 v237, s[70:71]
	s_add_u32 m0, s4, 0xc800
	v_mfma_f32_16x16x32_bf16 v[16:19], v[44:47], v[112:115], v[16:19]
	global_load_lds_dwordx4 v238, s[70:71]
	s_add_u32 m0, s4, 0xcc00
	v_mfma_f32_16x16x32_bf16 v[8:11], v[44:47], v[116:119], v[8:11]
	global_load_lds_dwordx4 v239, s[70:71]
	s_add_u32 s68, s68, 0x80
	s_addc_u32 s69, s69, 0
	s_add_u32 s70, s70, 0x80
	s_addc_u32 s71, s71, 0
	s_mov_b32 s32, 2
.Lg28l_loop:
	s_waitcnt vmcnt(8)
	s_barrier
	ds_read_b128 v[32:35], v252 offset:0
	ds_read_b128 v[104:107], v254 offset:32768
	ds_read_b128 v[108:111], v254 offset:34816
	ds_read_b128 v[112:115], v254 offset:36864
	ds_read_b128 v[116:119], v254 offset:38912
	ds_read_b128 v[36:39], v252 offset:2048
	ds_read_b128 v[40:43], v252 offset:4096
	ds_read_b128 v[44:47], v252 offset:6144
	v_mfma_f32_16x16x32_bf16 v[92:95], v[48:51], v[120:123], v[92:95]
	v_mfma_f32_16x16x32_bf16 v[88:91], v[48:51], v[124:127], v[88:91]
	v_mfma_f32_16x16x32_bf16 v[84:87], v[48:51], v[136:139], v[84:87]
	v_mfma_f32_16x16x32_bf16 v[80:83], v[48:51], v[144:147], v[80:83]
	v_mfma_f32_16x16x32_bf16 v[76:79], v[52:55], v[120:123], v[76:79]
	v_mfma_f32_16x16x32_bf16 v[72:75], v[52:55], v[124:127], v[72:75]
	v_mfma_f32_16x16x32_bf16 v[68:71], v[52:55], v[136:139], v[68:71]
	v_mfma_f32_16x16x32_bf16 v[60:63], v[52:55], v[144:147], v[60:63]
	v_mfma_f32_16x16x32_bf16 v[28:31], v[56:59], v[120:123], v[28:31]
	v_mfma_f32_16x16x32_bf16 v[20:23], v[56:59], v[124:127], v[20:23]
	v_mfma_f32_16x16x32_bf16 v[4:7], v[56:59], v[136:139], v[4:7]
	v_mfma_f32_16x16x32_bf16 v[12:15], v[56:59], v[144:147], v[12:15]
	v_mfma_f32_16x16x32_bf16 v[0:3], v[64:67], v[120:123], v[0:3]
	v_mfma_f32_16x16x32_bf16 v[24:27], v[64:67], v[124:127], v[24:27]
	v_mfma_f32_16x16x32_bf16 v[16:19], v[64:67], v[136:139], v[16:19]
	v_mfma_f32_16x16x32_bf16 v[8:11], v[64:67], v[144:147], v[8:11]
	ds_read_b128 v[48:51], v253 offset:0
	ds_read_b128 v[120:123], v255 offset:32768
	ds_read_b128 v[124:127], v255 offset:34816
	ds_read_b128 v[136:139], v255 offset:36864
	ds_read_b128 v[144:147], v255 offset:38912
	ds_read_b128 v[52:55], v253 offset:2048
	ds_read_b128 v[56:59], v253 offset:4096
	ds_read_b128 v[64:67], v253 offset:6144
	s_waitcnt lgkmcnt(14)
	v_mfma_f32_16x16x32_bf16 v[92:95], v[32:35], v[104:107], v[92:95]
	s_waitcnt lgkmcnt(13)
	v_mfma_f32_16x16x32_bf16 v[88:91], v[32:35], v[108:111], v[88:91]
	s_waitcnt lgkmcnt(12)
	v_mfma_f32_16x16x32_bf16 v[84:87], v[32:35], v[112:115], v[84:87]
	s_waitcnt lgkmcnt(11)
	v_mfma_f32_16x16x32_bf16 v[80:83], v[32:35], v[116:119], v[80:83]
	s_waitcnt lgkmcnt(10)
	v_mfma_f32_16x16x32_bf16 v[76:79], v[36:39], v[104:107], v[76:79]
	v_mfma_f32_16x16x32_bf16 v[72:75], v[36:39], v[108:111], v[72:75]
	v_mfma_f32_16x16x32_bf16 v[68:71], v[36:39], v[112:115], v[68:71]
	v_mfma_f32_16x16x32_bf16 v[60:63], v[36:39], v[116:119], v[60:63]
	s_waitcnt lgkmcnt(0)
	s_barrier
	s_add_u32 m0, s4, 0x0
	v_mfma_f32_16x16x32_bf16 v[28:31], v[40:43], v[104:107], v[28:31]
	global_load_lds_dwordx4 v236, s[68:69]
	s_add_u32 m0, s4, 0x400
	v_mfma_f32_16x16x32_bf16 v[20:23], v[40:43], v[108:111], v[20:23]
	global_load_lds_dwordx4 v237, s[68:69]
	s_add_u32 m0, s4, 0x800
	v_mfma_f32_16x16x32_bf16 v[4:7], v[40:43], v[112:115], v[4:7]
	global_load_lds_dwordx4 v238, s[68:69]
	s_add_u32 m0, s4, 0xc00
	v_mfma_f32_16x16x32_bf16 v[12:15], v[40:43], v[116:119], v[12:15]
	global_load_lds_dwordx4 v239, s[68:69]
	s_add_u32 m0, s4, 0x8000
	v_mfma_f32_16x16x32_bf16 v[0:3], v[44:47], v[104:107], v[0:3]
	global_load_lds_dwordx4 v236, s[70:71]
	s_add_u32 m0, s4, 0x8400
	v_mfma_f32_16x16x32_bf16 v[24:27], v[44:47], v[108:111], v[24:27]
	global_load_lds_dwordx4 v237, s[70:71]
	s_add_u32 m0, s4, 0x8800
	v_mfma_f32_16x16x32_bf16 v[16:19], v[44:47], v[112:115], v[16:19]
	global_load_lds_dwordx4 v238, s[70:71]
	s_add_u32 m0, s4, 0x8c00
	v_mfma_f32_16x16x32_bf16 v[8:11], v[44:47], v[116:119], v[8:11]
	global_load_lds_dwordx4 v239, s[70:71]
	s_add_u32 s68, s68, 0x80
	s_addc_u32 s69, s69, 0
	s_add_u32 s70, s70, 0x80
	s_addc_u32 s71, s71, 0
	s_waitcnt vmcnt(8)
	s_barrier
	ds_read_b128 v[32:35], v252 offset:16384
	ds_read_b128 v[104:107], v254 offset:49152
	ds_read_b128 v[108:111], v254 offset:51200
	ds_read_b128 v[112:115], v254 offset:53248
	ds_read_b128 v[116:119], v254 offset:55296
	ds_read_b128 v[36:39], v252 offset:18432
	ds_read_b128 v[40:43], v252 offset:20480
	ds_read_b128 v[44:47], v252 offset:22528
	v_mfma_f32_16x16x32_bf16 v[92:95], v[48:51], v[120:123], v[92:95]
	v_mfma_f32_16x16x32_bf16 v[88:91], v[48:51], v[124:127], v[88:91]
	v_mfma_f32_16x16x32_bf16 v[84:87], v[48:51], v[136:139], v[84:87]
	v_mfma_f32_16x16x32_bf16 v[80:83], v[48:51], v[144:147], v[80:83]
	v_mfma_f32_16x16x32_bf16 v[76:79], v[52:55], v[120:123], v[76:79]
	v_mfma_f32_16x16x32_bf16 v[72:75], v[52:55], v[124:127], v[72:75]
	v_mfma_f32_16x16x32_bf16 v[68:71], v[52:55], v[136:139], v[68:71]
	v_mfma_f32_16x16x32_bf16 v[60:63], v[52:55], v[144:147], v[60:63]
	v_mfma_f32_16x16x32_bf16 v[28:31], v[56:59], v[120:123], v[28:31]
	v_mfma_f32_16x16x32_bf16 v[20:23], v[56:59], v[124:127], v[20:23]
	v_mfma_f32_16x16x32_bf16 v[4:7], v[56:59], v[136:139], v[4:7]
	v_mfma_f32_16x16x32_bf16 v[12:15], v[56:59], v[144:147], v[12:15]
	v_mfma_f32_16x16x32_bf16 v[0:3], v[64:67], v[120:123], v[0:3]
	v_mfma_f32_16x16x32_bf16 v[24:27], v[64:67], v[124:127], v[24:27]
	v_mfma_f32_16x16x32_bf16 v[16:19], v[64:67], v[136:139], v[16:19]
	v_mfma_f32_16x16x32_bf16 v[8:11], v[64:67], v[144:147], v[8:11]
	ds_read_b128 v[48:51], v253 offset:16384
	ds_read_b128 v[120:123], v255 offset:49152
	ds_read_b128 v[124:127], v255 offset:51200
	ds_read_b128 v[136:139], v255 offset:53248
	ds_read_b128 v[144:147], v255 offset:55296
	ds_read_b128 v[52:55], v253 offset:18432
	ds_read_b128 v[56:59], v253 offset:20480
	ds_read_b128 v[64:67], v253 offset:22528
	s_waitcnt lgkmcnt(14)
	v_mfma_f32_16x16x32_bf16 v[92:95], v[32:35], v[104:107], v[92:95]
	s_waitcnt lgkmcnt(13)
	v_mfma_f32_16x16x32_bf16 v[88:91], v[32:35], v[108:111], v[88:91]
	s_waitcnt lgkmcnt(12)
	v_mfma_f32_16x16x32_bf16 v[84:87], v[32:35], v[112:115], v[84:87]
	s_waitcnt lgkmcnt(11)
	v_mfma_f32_16x16x32_bf16 v[80:83], v[32:35], v[116:119], v[80:83]
	s_waitcnt lgkmcnt(10)
	v_mfma_f32_16x16x32_bf16 v[76:79], v[36:39], v[104:107], v[76:79]
	v_mfma_f32_16x16x32_bf16 v[72:75], v[36:39], v[108:111], v[72:75]
	v_mfma_f32_16x16x32_bf16 v[68:71], v[36:39], v[112:115], v[68:71]
	v_mfma_f32_16x16x32_bf16 v[60:63], v[36:39], v[116:119], v[60:63]
	s_waitcnt lgkmcnt(0)
	s_barrier
	s_add_u32 m0, s4, 0x4000
	v_mfma_f32_16x16x32_bf16 v[28:31], v[40:43], v[104:107], v[28:31]
	global_load_lds_dwordx4 v236, s[68:69]
	s_add_u32 m0, s4, 0x4400
	v_mfma_f32_16x16x32_bf16 v[20:23], v[40:43], v[108:111], v[20:23]
	global_load_lds_dwordx4 v237, s[68:69]
	s_add_u32 m0, s4, 0x4800
	v_mfma_f32_16x16x32_bf16 v[4:7], v[40:43], v[112:115], v[4:7]
	global_load_lds_dwordx4 v238, s[68:69]
	s_add_u32 m0, s4, 0x4c00
	v_mfma_f32_16x16x32_bf16 v[12:15], v[40:43], v[116:119], v[12:15]
	global_load_lds_dwordx4 v239, s[68:69]
	s_add_u32 m0, s4, 0xc000
	v_mfma_f32_16x16x32_bf16 v[0:3], v[44:47], v[104:107], v[0:3]
	global_load_lds_dwordx4 v236, s[70:71]
	s_add_u32 m0, s4, 0xc400
	v_mfma_f32_16x16x32_bf16 v[24:27], v[44:47], v[108:111], v[24:27]
	global_load_lds_dwordx4 v237, s[70:71]
	s_add_u32 m0, s4, 0xc800
	v_mfma_f32_16x16x32_bf16 v[16:19], v[44:47], v[112:115], v[16:19]
	global_load_lds_dwordx4 v238, s[70:71]
	s_add_u32 m0, s4, 0xcc00
	v_mfma_f32_16x16x32_bf16 v[8:11], v[44:47], v[116:119], v[8:11]
	global_load_lds_dwordx4 v239, s[70:71]
	s_add_u32 s68, s68, 0x80
	s_addc_u32 s69, s69, 0
	s_add_u32 s70, s70, 0x80
	s_addc_u32 s71, s71, 0
	s_sub_u32 s32, s32, 1
	s_cmp_lg_u32 s32, 0
	s_cbranch_scc1 .Lg28l_loop
	s_waitcnt vmcnt(8)
	s_barrier
	ds_read_b128 v[32:35], v252 offset:0
	ds_read_b128 v[104:107], v254 offset:32768
	ds_read_b128 v[108:111], v254 offset:34816
	ds_read_b128 v[112:115], v254 offset:36864
	ds_read_b128 v[116:119], v254 offset:38912
	ds_read_b128 v[36:39], v252 offset:2048
	ds_read_b128 v[40:43], v252 offset:4096
	ds_read_b128 v[44:47], v252 offset:6144
	v_mfma_f32_16x16x32_bf16 v[92:95], v[48:51], v[120:123], v[92:95]
	v_mfma_f32_16x16x32_bf16 v[88:91], v[48:51], v[124:127], v[88:91]
	v_mfma_f32_16x16x32_bf16 v[84:87], v[48:51], v[136:139], v[84:87]
	v_mfma_f32_16x16x32_bf16 v[80:83], v[48:51], v[144:147], v[80:83]
	v_mfma_f32_16x16x32_bf16 v[76:79], v[52:55], v[120:123], v[76:79]
	v_mfma_f32_16x16x32_bf16 v[72:75], v[52:55], v[124:127], v[72:75]
	v_mfma_f32_16x16x32_bf16 v[68:71], v[52:55], v[136:139], v[68:71]
	v_mfma_f32_16x16x32_bf16 v[60:63], v[52:55], v[144:147], v[60:63]
	v_mfma_f32_16x16x32_bf16 v[28:31], v[56:59], v[120:123], v[28:31]
	v_mfma_f32_16x16x32_bf16 v[20:23], v[56:59], v[124:127], v[20:23]
	v_mfma_f32_16x16x32_bf16 v[4:7], v[56:59], v[136:139], v[4:7]
	v_mfma_f32_16x16x32_bf16 v[12:15], v[56:59], v[144:147], v[12:15]
	v_mfma_f32_16x16x32_bf16 v[0:3], v[64:67], v[120:123], v[0:3]
	v_mfma_f32_16x16x32_bf16 v[24:27], v[64:67], v[124:127], v[24:27]
	v_mfma_f32_16x16x32_bf16 v[16:19], v[64:67], v[136:139], v[16:19]
	v_mfma_f32_16x16x32_bf16 v[8:11], v[64:67], v[144:147], v[8:11]
	ds_read_b128 v[48:51], v253 offset:0
	ds_read_b128 v[120:123], v255 offset:32768
	ds_read_b128 v[124:127], v255 offset:34816
	ds_read_b128 v[136:139], v255 offset:36864
	ds_read_b128 v[144:147], v255 offset:38912
	ds_read_b128 v[52:55], v253 offset:2048
	ds_read_b128 v[56:59], v253 offset:4096
	ds_read_b128 v[64:67], v253 offset:6144
	s_waitcnt lgkmcnt(14)
	v_mfma_f32_16x16x32_bf16 v[92:95], v[32:35], v[104:107], v[92:95]
	s_waitcnt lgkmcnt(13)
	v_mfma_f32_16x16x32_bf16 v[88:91], v[32:35], v[108:111], v[88:91]
	s_waitcnt lgkmcnt(12)
	v_mfma_f32_16x16x32_bf16 v[84:87], v[32:35], v[112:115], v[84:87]
	s_waitcnt lgkmcnt(11)
	v_mfma_f32_16x16x32_bf16 v[80:83], v[32:35], v[116:119], v[80:83]
	s_waitcnt lgkmcnt(10)
	v_mfma_f32_16x16x32_bf16 v[76:79], v[36:39], v[104:107], v[76:79]
	v_mfma_f32_16x16x32_bf16 v[72:75], v[36:39], v[108:111], v[72:75]
	v_mfma_f32_16x16x32_bf16 v[68:71], v[36:39], v[112:115], v[68:71]
	v_mfma_f32_16x16x32_bf16 v[60:63], v[36:39], v[116:119], v[60:63]
	s_waitcnt lgkmcnt(0)
	s_barrier
	v_mfma_f32_16x16x32_bf16 v[28:31], v[40:43], v[104:107], v[28:31]
	v_mfma_f32_16x16x32_bf16 v[20:23], v[40:43], v[108:111], v[20:23]
	v_mfma_f32_16x16x32_bf16 v[4:7], v[40:43], v[112:115], v[4:7]
	v_mfma_f32_16x16x32_bf16 v[12:15], v[40:43], v[116:119], v[12:15]
	v_mfma_f32_16x16x32_bf16 v[0:3], v[44:47], v[104:107], v[0:3]
	v_mfma_f32_16x16x32_bf16 v[24:27], v[44:47], v[108:111], v[24:27]
	v_mfma_f32_16x16x32_bf16 v[16:19], v[44:47], v[112:115], v[16:19]
	v_mfma_f32_16x16x32_bf16 v[8:11], v[44:47], v[116:119], v[8:11]
	s_waitcnt vmcnt(0)
	s_barrier
	ds_read_b128 v[32:35], v252 offset:16384
	ds_read_b128 v[104:107], v254 offset:49152
	ds_read_b128 v[108:111], v254 offset:51200
	ds_read_b128 v[112:115], v254 offset:53248
	ds_read_b128 v[116:119], v254 offset:55296
	ds_read_b128 v[36:39], v252 offset:18432
	ds_read_b128 v[40:43], v252 offset:20480
	ds_read_b128 v[44:47], v252 offset:22528
	v_mfma_f32_16x16x32_bf16 v[92:95], v[48:51], v[120:123], v[92:95]
	v_mfma_f32_16x16x32_bf16 v[88:91], v[48:51], v[124:127], v[88:91]
	v_mfma_f32_16x16x32_bf16 v[84:87], v[48:51], v[136:139], v[84:87]
	v_mfma_f32_16x16x32_bf16 v[80:83], v[48:51], v[144:147], v[80:83]
	v_mfma_f32_16x16x32_bf16 v[76:79], v[52:55], v[120:123], v[76:79]
	v_mfma_f32_16x16x32_bf16 v[72:75], v[52:55], v[124:127], v[72:75]
	v_mfma_f32_16x16x32_bf16 v[68:71], v[52:55], v[136:139], v[68:71]
	v_mfma_f32_16x16x32_bf16 v[60:63], v[52:55], v[144:147], v[60:63]
	v_mfma_f32_16x16x32_bf16 v[28:31], v[56:59], v[120:123], v[28:31]
	v_mfma_f32_16x16x32_bf16 v[20:23], v[56:59], v[124:127], v[20:23]
	v_mfma_f32_16x16x32_bf16 v[4:7], v[56:59], v[136:139], v[4:7]
	v_mfma_f32_16x16x32_bf16 v[12:15], v[56:59], v[144:147], v[12:15]
	v_mfma_f32_16x16x32_bf16 v[0:3], v[64:67], v[120:123], v[0:3]
	v_mfma_f32_16x16x32_bf16 v[24:27], v[64:67], v[124:127], v[24:27]
	v_mfma_f32_16x16x32_bf16 v[16:19], v[64:67], v[136:139], v[16:19]
	v_mfma_f32_16x16x32_bf16 v[8:11], v[64:67], v[144:147], v[8:11]
	ds_read_b128 v[48:51], v253 offset:16384
	ds_read_b128 v[120:123], v255 offset:49152
	ds_read_b128 v[124:127], v255 offset:51200
	ds_read_b128 v[136:139], v255 offset:53248
	ds_read_b128 v[144:147], v255 offset:55296
	ds_read_b128 v[52:55], v253 offset:18432
	ds_read_b128 v[56:59], v253 offset:20480
	ds_read_b128 v[64:67], v253 offset:22528
	s_waitcnt lgkmcnt(14)
	v_mfma_f32_16x16x32_bf16 v[92:95], v[32:35], v[104:107], v[92:95]
	s_waitcnt lgkmcnt(13)
	v_mfma_f32_16x16x32_bf16 v[88:91], v[32:35], v[108:111], v[88:91]
	s_waitcnt lgkmcnt(12)
	v_mfma_f32_16x16x32_bf16 v[84:87], v[32:35], v[112:115], v[84:87]
	s_waitcnt lgkmcnt(11)
	v_mfma_f32_16x16x32_bf16 v[80:83], v[32:35], v[116:119], v[80:83]
	s_waitcnt lgkmcnt(10)
	v_mfma_f32_16x16x32_bf16 v[76:79], v[36:39], v[104:107], v[76:79]
	v_mfma_f32_16x16x32_bf16 v[72:75], v[36:39], v[108:111], v[72:75]
	v_mfma_f32_16x16x32_bf16 v[68:71], v[36:39], v[112:115], v[68:71]
	v_mfma_f32_16x16x32_bf16 v[60:63], v[36:39], v[116:119], v[60:63]
	s_waitcnt lgkmcnt(0)
	s_barrier
	v_mfma_f32_16x16x32_bf16 v[28:31], v[40:43], v[104:107], v[28:31]
	v_mfma_f32_16x16x32_bf16 v[20:23], v[40:43], v[108:111], v[20:23]
	v_mfma_f32_16x16x32_bf16 v[4:7], v[40:43], v[112:115], v[4:7]
	v_mfma_f32_16x16x32_bf16 v[12:15], v[40:43], v[116:119], v[12:15]
	v_mfma_f32_16x16x32_bf16 v[0:3], v[44:47], v[104:107], v[0:3]
	v_mfma_f32_16x16x32_bf16 v[24:27], v[44:47], v[108:111], v[24:27]
	v_mfma_f32_16x16x32_bf16 v[16:19], v[44:47], v[112:115], v[16:19]
	v_mfma_f32_16x16x32_bf16 v[8:11], v[44:47], v[116:119], v[8:11]
	v_mfma_f32_16x16x32_bf16 v[92:95], v[48:51], v[120:123], v[92:95]
	v_mfma_f32_16x16x32_bf16 v[88:91], v[48:51], v[124:127], v[88:91]
	v_mfma_f32_16x16x32_bf16 v[84:87], v[48:51], v[136:139], v[84:87]
	v_mfma_f32_16x16x32_bf16 v[80:83], v[48:51], v[144:147], v[80:83]
	v_mfma_f32_16x16x32_bf16 v[76:79], v[52:55], v[120:123], v[76:79]
	v_mfma_f32_16x16x32_bf16 v[72:75], v[52:55], v[124:127], v[72:75]
	v_mfma_f32_16x16x32_bf16 v[68:71], v[52:55], v[136:139], v[68:71]
	v_mfma_f32_16x16x32_bf16 v[60:63], v[52:55], v[144:147], v[60:63]
	v_mfma_f32_16x16x32_bf16 v[28:31], v[56:59], v[120:123], v[28:31]
	v_mfma_f32_16x16x32_bf16 v[20:23], v[56:59], v[124:127], v[20:23]
	v_mfma_f32_16x16x32_bf16 v[4:7], v[56:59], v[136:139], v[4:7]
	v_mfma_f32_16x16x32_bf16 v[12:15], v[56:59], v[144:147], v[12:15]
	v_mfma_f32_16x16x32_bf16 v[0:3], v[64:67], v[120:123], v[0:3]
	v_mfma_f32_16x16x32_bf16 v[24:27], v[64:67], v[124:127], v[24:27]
	v_mfma_f32_16x16x32_bf16 v[16:19], v[64:67], v[136:139], v[16:19]
	v_mfma_f32_16x16x32_bf16 v[8:11], v[64:67], v[144:147], v[8:11]
	s_nop 7
	s_nop 1
.Lg28_join:
	v_add_u32_e32 v32, s66, v140
	v_lshl_or_b32 v96, s65, 8, v141
	v_ashrrev_i32_e32 v33, 31, v32
	v_lshl_add_u64 v[34:35], v[98:99], 0, v[96:97]
	v_lshlrev_b64 v[32:33], 11, v[32:33]
	v_cvt_pk_bf16_f32 v36, v92, s0
	v_lshl_add_u64 v[32:33], v[34:35], 0, v[32:33]
	global_store_short v[32:33], v36, off
	v_add_co_u32_e32 v36, vcc, 0x1000, v32
	v_cvt_pk_bf16_f32 v38, v94, s0
	s_nop 0
	v_addc_co_u32_e32 v37, vcc, 0, v33, vcc
	v_cvt_pk_bf16_f32 v40, v95, s0
	global_store_short v[36:37], v38, off
	global_store_short v[36:37], v40, off offset:2048
	v_cvt_pk_bf16_f32 v36, v88, s0
	v_cvt_pk_bf16_f32 v34, v93, s0
	global_store_short v[32:33], v36, off offset:32
	v_cvt_pk_bf16_f32 v36, v89, s0
	global_store_short v[32:33], v34, off offset:2048
	v_lshl_add_u64 v[34:35], v[32:33], 0, s[8:9]
	global_store_short v[32:33], v36, off offset:2080
	v_cvt_pk_bf16_f32 v36, v90, s0
	v_lshl_add_u64 v[38:39], v[32:33], 0, s[10:11]
	global_store_short v[34:35], v36, off offset:32
	v_cvt_pk_bf16_f32 v36, v91, s0
	global_store_short v[38:39], v36, off offset:32
	v_cvt_pk_bf16_f32 v36, v84, s0
	global_store_short v[32:33], v36, off offset:64
	v_cvt_pk_bf16_f32 v36, v85, s0
	global_store_short v[32:33], v36, off offset:2112
	v_cvt_pk_bf16_f32 v36, v86, s0
	global_store_short v[34:35], v36, off offset:64
	v_cvt_pk_bf16_f32 v36, v87, s0
	global_store_short v[38:39], v36, off offset:64
	v_cvt_pk_bf16_f32 v36, v80, s0
	global_store_short v[32:33], v36, off offset:96
	v_cvt_pk_bf16_f32 v36, v81, s0
	global_store_short v[32:33], v36, off offset:2144
	v_cvt_pk_bf16_f32 v36, v82, s0
	global_store_short v[34:35], v36, off offset:96
	v_add_co_u32_e32 v36, vcc, s51, v32
	v_cvt_pk_bf16_f32 v34, v83, s0
	s_nop 0
	v_addc_co_u32_e32 v37, vcc, 0, v33, vcc
	global_store_short v[38:39], v34, off offset:96
	v_add_co_u32_e32 v38, vcc, s54, v32
	v_cvt_pk_bf16_f32 v42, v77, s0
	v_cvt_pk_bf16_f32 v40, v76, s0
	v_addc_co_u32_e32 v39, vcc, 0, v33, vcc
	global_store_short v[36:37], v42, off offset:2048
	v_cvt_pk_bf16_f32 v42, v78, s0
	s_waitcnt vmcnt(19)
	v_cvt_pk_bf16_f32 v44, v79, s0
	v_lshl_add_u64 v[34:35], v[32:33], 0, s[12:13]
	global_store_short v[38:39], v40, off offset:-4096
	global_store_short v[38:39], v42, off
	global_store_short v[38:39], v44, off offset:2048
	v_cvt_pk_bf16_f32 v38, v72, s0
	v_lshl_add_u64 v[40:41], v[32:33], 0, s[14:15]
	global_store_short v[34:35], v38, off offset:32
	v_cvt_pk_bf16_f32 v38, v73, s0
	v_lshl_add_u64 v[36:37], v[32:33], 0, s[16:17]
	global_store_short v[40:41], v38, off offset:32
	v_cvt_pk_bf16_f32 v38, v74, s0
	v_lshl_add_u64 v[42:43], v[32:33], 0, s[18:19]
	global_store_short v[36:37], v38, off offset:32
	v_cvt_pk_bf16_f32 v38, v75, s0
	global_store_short v[42:43], v38, off offset:32
	v_cvt_pk_bf16_f32 v38, v68, s0
	global_store_short v[34:35], v38, off offset:64
	v_cvt_pk_bf16_f32 v38, v69, s0
	global_store_short v[40:41], v38, off offset:64
	v_cvt_pk_bf16_f32 v38, v70, s0
	global_store_short v[36:37], v38, off offset:64
	v_cvt_pk_bf16_f32 v38, v71, s0
	global_store_short v[42:43], v38, off offset:64
	v_cvt_pk_bf16_f32 v38, v60, s0
	global_store_short v[34:35], v38, off offset:96
	v_cvt_pk_bf16_f32 v34, v61, s0
	global_store_short v[40:41], v34, off offset:96
	v_cvt_pk_bf16_f32 v34, v62, s0
	global_store_short v[36:37], v34, off offset:96
	v_add_co_u32_e32 v36, vcc, s55, v32
	v_cvt_pk_bf16_f32 v34, v63, s0
	s_nop 0
	v_addc_co_u32_e32 v37, vcc, 0, v33, vcc
	v_add_co_u32_e32 v38, vcc, s59, v32
	global_store_short v[42:43], v34, off offset:96
	v_cvt_pk_bf16_f32 v28, v28, s0
	v_lshl_add_u64 v[34:35], v[32:33], 0, s[20:21]
	v_addc_co_u32_e32 v39, vcc, 0, v33, vcc
	v_cvt_pk_bf16_f32 v4, v4, s0
	global_store_short v[38:39], v28, off offset:-4096
	v_cvt_pk_bf16_f32 v40, v29, s0
	v_lshl_add_u64 v[28:29], v[32:33], 0, s[22:23]
	global_store_short v[34:35], v4, off offset:64
	v_cvt_pk_bf16_f32 v4, v5, s0
	global_store_short v[36:37], v40, off offset:2048
	v_cvt_pk_bf16_f32 v30, v30, s0
	v_lshl_add_u64 v[36:37], v[32:33], 0, s[24:25]
	global_store_short v[28:29], v4, off offset:64
	v_cvt_pk_bf16_f32 v4, v6, s0
	global_store_short v[38:39], v30, off
	v_cvt_pk_bf16_f32 v40, v31, s0
	v_lshl_add_u64 v[30:31], v[32:33], 0, s[26:27]
	global_store_short v[36:37], v4, off offset:64
	v_cvt_pk_bf16_f32 v4, v7, s0
	global_store_short v[30:31], v4, off offset:64
	v_cvt_pk_bf16_f32 v4, v12, s0
	v_add_co_u32_e32 v6, vcc, s62, v32
	global_store_short v[34:35], v4, off offset:96
	v_cvt_pk_bf16_f32 v4, v13, s0
	v_addc_co_u32_e32 v7, vcc, 0, v33, vcc
	global_store_short v[28:29], v4, off offset:96
	v_cvt_pk_bf16_f32 v4, v14, s0
	v_add_co_u32_e32 v12, vcc, s63, v32
	v_cvt_pk_bf16_f32 v14, v1, s0
	global_store_short v[36:37], v4, off offset:96
	v_cvt_pk_bf16_f32 v4, v15, s0
	v_cvt_pk_bf16_f32 v0, v0, s0
	v_addc_co_u32_e32 v13, vcc, 0, v33, vcc
	global_store_short v[6:7], v14, off offset:2048
	v_cvt_pk_bf16_f32 v2, v2, s0
	v_cvt_pk_bf16_f32 v14, v3, s0
	global_store_short v[30:31], v4, off offset:96
	v_lshl_add_u64 v[4:5], v[32:33], 0, s[28:29]
	global_store_short v[12:13], v0, off offset:-4096
	global_store_short v[12:13], v2, off
	global_store_short v[12:13], v14, off offset:2048
	v_cvt_pk_bf16_f32 v12, v24, s0
	v_lshl_add_u64 v[0:1], v[32:33], 0, s[30:31]
	global_store_short v[4:5], v12, off offset:32
	v_cvt_pk_bf16_f32 v12, v25, s0
	v_lshl_add_u64 v[6:7], v[32:33], 0, s[34:35]
	global_store_short v[0:1], v12, off offset:32
	v_cvt_pk_bf16_f32 v12, v26, s0
	v_lshl_add_u64 v[2:3], v[32:33], 0, s[36:37]
	global_store_short v[6:7], v12, off offset:32
	v_cvt_pk_bf16_f32 v12, v27, s0
	v_cvt_pk_bf16_f32 v20, v20, s0
	global_store_short v[2:3], v12, off offset:32
	v_cvt_pk_bf16_f32 v12, v16, s0
	v_cvt_pk_bf16_f32 v8, v8, s0
	global_store_short v[34:35], v20, off offset:32
	v_cvt_pk_bf16_f32 v20, v21, s0
	global_store_short v[4:5], v12, off offset:64
	v_cvt_pk_bf16_f32 v12, v17, s0
	global_store_short v[4:5], v8, off offset:96
	v_cvt_pk_bf16_f32 v4, v9, s0
	global_store_short v[28:29], v20, off offset:32
	v_cvt_pk_bf16_f32 v20, v22, s0
	global_store_short v[0:1], v12, off offset:64
	v_cvt_pk_bf16_f32 v12, v18, s0
	global_store_short v[0:1], v4, off offset:96
	v_cvt_pk_bf16_f32 v0, v10, s0
	s_add_i32 s64, s64, s2
	global_store_short v[36:37], v20, off offset:32
	v_cvt_pk_bf16_f32 v20, v23, s0
	global_store_short v[6:7], v12, off offset:64
	v_cvt_pk_bf16_f32 v12, v19, s0
	global_store_short v[6:7], v0, off offset:96
	v_cvt_pk_bf16_f32 v0, v11, s0
	s_cmpk_lt_i32 s64, 0x200
	global_store_short v[38:39], v40, off offset:2048
	global_store_short v[30:31], v20, off offset:32
	global_store_short v[2:3], v12, off offset:64
	global_store_short v[2:3], v0, off offset:96
	s_cbranch_scc1 .LBB0_2658
